# in-proj k/v tile epilogue: pair exchange via DPP quad_perm + one v_perm_b32 per dword instead of ds_bpermute + exec-masked diamonds (bit-identical); on top of v23
# baseline (speedup 1.0000x reference)
;     __host__ __device__ bool next(int i, Unit& u) const {
;         const long L = (long)i * G + c; if (L >= nwg) return false;
;         int wgid = (int)L; { const int q = nwg / NXCD, r = nwg % NXCD, xcd = wgid % NXCD, off = wgid / NXCD; wgid = (xcd < r ? xcd * (q + 1) : r * (q + 1) + (xcd - r) * q) + off; }
;         const int nig = WGM * nN, gid = wgid / nig, fm = gid * WGM, gsz = (nM - fm) < WGM ? (nM - fm) : WGM;
;         u.pm = fm + ((wgid % nig) % gsz); u.pn = (wgid % nig) / gsz; return true;
;     __device__ __forceinline__ void operator()(const f32x4 (&acc)[2][2][4][2], const Unit& u, int wr, int wc, int fr, int fq) const {
;     ...
;                             for (int q = 0; q < 4; ++q) { const unsigned mine = w[q], other = (unsigned)__shfl_xor((int)mine, 1);
;                                 const unsigned pr = odd ? ((other >> 16) | (mine & 0xffff0000u)) : ((mine & 0xffffu) | (other << 16));
.LBB0_252:
	s_cmp_le_i32 s28, s8
	s_cselect_b64 s[2:3], -1, 0
	s_and_b64 s[0:1], s[2:3], s[0:1]
	s_andn2_b64 vcc, exec, s[0:1]
	s_cbranch_vccnz .LBB0_834
	v_and_b32_e32 v250, 1, v160
	v_sub_u32_e32 v250, 0, v250
	v_and_b32_e32 v250, 0x6060606, v250
	v_xor_b32_e32 v250, 0x5040100, v250
	s_mov_b32 s12, s30
	s_mov_b32 s63, s10
	v_mov_b32_e32 v0, s33
	ds_read_b64 v[0:1], v0
	v_mov_b32_e32 v8, v160
	s_cmpk_lt_i32 s63, 0x700
	s_cselect_b64 s[0:1], -1, 0
	s_waitcnt lgkmcnt(0)
	v_readfirstlane_b32 s86, v0
	v_readfirstlane_b32 s87, v1
	s_cmpk_gt_i32 s63, 0x6ff
	v_readfirstlane_b32 s2, v8
	s_cbranch_scc1 .LBB0_255
	s_ashr_i32 s3, s63, 31
	s_lshr_b32 s3, s3, 29
	s_add_i32 s3, s63, s3
	s_ashr_i32 s4, s3, 3
	s_and_b32 s3, s3, -8
	s_sub_i32 s3, s63, s3
	s_cmp_lt_i32 s3, 0
	s_movk_i32 s5, 0xe1
	s_cselect_b32 s5, s5, 0xe0
	s_mul_i32 s3, s3, s5
	s_add_i32 s3, s3, s4
	s_mul_hi_i32 s4, s3, 0x92492493
	s_add_i32 s4, s4, s3
	s_lshr_b32 s5, s4, 31
	s_ashr_i32 s4, s4, 5
	s_add_i32 s4, s4, s5
	s_lshl_b32 s5, s4, 2
	s_mul_i32 s4, s4, 56
	s_sub_i32 s3, s3, s4
	s_bfe_i32 s4, s3, 0x80000
	s_bfe_u32 s4, s4, 0x2000d
	s_add_i32 s4, s3, s4
	s_bfe_i32 s6, s4, 0x80000
	s_and_b32 s4, s4, 0xfc
	s_sub_i32 s3, s3, s4
	s_sext_i32_i16 s6, s6
	s_sext_i32_i8 s3, s3
	s_add_i32 s78, s5, s3
	s_ashr_i32 s6, s6, 2

; __device__ __forceinline__ unsigned cvt_pk_bf16(float lo, float hi) { unsigned r; asm volatile("v_cvt_pk_bf16_f32 %0, %1, %2" : "=v"(r) : "v"(lo), "v"(hi)); return r; }
;     __device__ __forceinline__ void operator()(const f32x4 (&acc)[2][2][4][2], const Unit& u, int wr, int wc, int fr, int fq) const {
;     ...
;         } else if (u.pn >= 12) {
;             const int odd = fr & 1;
; #pragma unroll
;             for (int ai = 0; ai < 2; ++ai)
; #pragma unroll
;                 for (int m = 0; m < 4; ++m) { const int tokrow = row0 + ai * HALF + m * 16;
; #pragma unroll
;                     for (int bj = 0; bj < 2; ++bj) {
;                         const f32x4 v0 = acc[ai][bj][m][0], v1 = acc[ai][bj][m][1];
;                         u32x4 w; w.x = cvt_pk_bf16(v0[0], v0[1]); w.y = cvt_pk_bf16(v0[2], v0[3]); w.z = cvt_pk_bf16(v1[0], v1[1]); w.w = cvt_pk_bf16(v1[2], v1[3]);
;                         bf16_t* vt = KT + (size_t)(512 + (u.pn - 12) * BM + bj * HALF + wc * 32 + 8 * fq + odd) * ldk + (tokrow - odd);
; #pragma unroll
;                         for (int q = 0; q < 4; ++q) { const unsigned mine = w[q], other = (unsigned)__shfl_xor((int)mine, 1);
;                             const unsigned pr = odd ? ((other >> 16) | (mine & 0xffff0000u)) : ((mine & 0xffffu) | (other << 16));
;                             *(unsigned*)(vt + (size_t)(2 * q) * ldk) = pr; }
;                     } }
.LBB0_274:
	s_andn2_b64 vcc, exec, s[16:17]
	s_cbranch_vccnz .LBB0_532
	v_cmp_lt_i32_e32 vcc, v228, v222
	v_cvt_pk_bf16_f32 v128, v124, v125
	v_cvt_pk_bf16_f32 v135, v126, v127
	v_cvt_pk_bf16_f32 v133, v120, v121
	v_cvt_pk_bf16_f32 v132, v122, v123
	s_nop 1
	v_cndmask_b32_e32 v129, v221, v228, vcc
	v_lshlrev_b32_e32 v134, 2, v129
	s_nop 1
	v_mov_b32_dpp v129, v128 quad_perm:[1,0,3,2] row_mask:0xf bank_mask:0xf
	v_perm_b32 v136, v129, v128, v250
	v_sub_u32_e32 v130, v210, v176
	v_add_u32_e32 v137, s7, v205
	s_waitcnt lgkmcnt(0)
	v_mov_b64_e32 v[128:129], s[66:67]
	v_ashrrev_i32_e32 v131, 31, v130
	v_mad_i64_i32 v[128:129], s[16:17], v137, s45, v[128:129]
	v_lshl_add_u64 v[128:129], v[130:131], 1, v[128:129]
	global_store_dword v[128:129], v136, off
	s_nop 1
	v_mov_b32_dpp v136, v135 quad_perm:[1,0,3,2] row_mask:0xf bank_mask:0xf
	v_perm_b32 v137, v136, v135, v250
	s_nop 1
	v_mov_b32_dpp v135, v133 quad_perm:[1,0,3,2] row_mask:0xf bank_mask:0xf
	v_add_co_u32_e32 v138, vcc, 0x22000, v128
	s_nop 1
	v_addc_co_u32_e32 v139, vcc, 0, v129, vcc
	global_store_dword v[138:139], v137, off offset:256
	v_perm_b32 v136, v135, v133, v250
	s_nop 1
	v_mov_b32_dpp v133, v132 quad_perm:[1,0,3,2] row_mask:0xf bank_mask:0xf
	v_add_co_u32_e32 v138, vcc, 0x44000, v128
	s_nop 1
	v_addc_co_u32_e32 v139, vcc, 0, v129, vcc
	s_waitcnt lgkmcnt(0)
	global_store_dword v[138:139], v136, off offset:512
	v_perm_b32 v135, v133, v132, v250
	v_add_co_u32_e32 v132, vcc, 0x66000, v128
	s_nop 1
	v_addc_co_u32_e32 v133, vcc, 0, v129, vcc
	global_store_dword v[132:133], v135, off offset:768
	v_cvt_pk_bf16_f32 v136, v116, v117
	s_nop 1
	v_mov_b32_dpp v138, v136 quad_perm:[1,0,3,2] row_mask:0xf bank_mask:0xf
	v_cvt_pk_bf16_f32 v135, v118, v119
	v_cvt_pk_bf16_f32 v133, v112, v113
	v_cvt_pk_bf16_f32 v132, v114, v115
	v_perm_b32 v137, v138, v136, v250
	v_add_u32_e32 v136, s7, v206
	s_waitcnt lgkmcnt(0)
	v_mov_b64_e32 v[138:139], s[66:67]
	v_mad_i64_i32 v[138:139], s[16:17], v136, s45, v[138:139]
	s_nop 1
	v_mov_b32_dpp v136, v135 quad_perm:[1,0,3,2] row_mask:0xf bank_mask:0xf
	v_lshl_add_u64 v[130:131], v[130:131], 1, v[138:139]
	global_store_dword v[130:131], v137, off
	v_perm_b32 v137, v136, v135, v250
	s_nop 1
	v_mov_b32_dpp v135, v133 quad_perm:[1,0,3,2] row_mask:0xf bank_mask:0xf
	v_add_co_u32_e32 v138, vcc, 0x22000, v130
	s_nop 1
	v_addc_co_u32_e32 v139, vcc, 0, v131, vcc
	global_store_dword v[138:139], v137, off offset:256
	v_perm_b32 v136, v135, v133, v250
	s_nop 1
	v_mov_b32_dpp v133, v132 quad_perm:[1,0,3,2] row_mask:0xf bank_mask:0xf
	v_add_co_u32_e32 v138, vcc, 0x44000, v130
	s_nop 1
	v_addc_co_u32_e32 v139, vcc, 0, v131, vcc
	s_waitcnt lgkmcnt(0)
	global_store_dword v[138:139], v136, off offset:512
	v_perm_b32 v135, v133, v132, v250
	v_add_co_u32_e32 v132, vcc, 0x66000, v130
	s_nop 1
	v_addc_co_u32_e32 v133, vcc, 0, v131, vcc
	global_store_dword v[132:133], v135, off offset:768
	v_cvt_pk_bf16_f32 v133, v108, v109
	s_nop 1
	v_mov_b32_dpp v138, v133 quad_perm:[1,0,3,2] row_mask:0xf bank_mask:0xf
	v_cvt_pk_bf16_f32 v132, v110, v111
	v_cvt_pk_bf16_f32 v136, v104, v105
	v_cvt_pk_bf16_f32 v135, v106, v107
	v_perm_b32 v137, v138, v133, v250
	s_nop 1
	v_mov_b32_dpp v133, v132 quad_perm:[1,0,3,2] row_mask:0xf bank_mask:0xf
	global_store_dword v[128:129], v137, off offset:32
	v_perm_b32 v137, v133, v132, v250
	s_waitcnt lgkmcnt(0)
	v_lshl_add_u64 v[132:133], v[128:129], 0, 32
	v_add_co_u32_e32 v138, vcc, 0x22000, v132
	s_nop 1
	v_addc_co_u32_e32 v139, vcc, 0, v133, vcc
	global_store_dword v[138:139], v137, off offset:256
	s_nop 1
	v_mov_b32_dpp v137, v136 quad_perm:[1,0,3,2] row_mask:0xf bank_mask:0xf
	v_perm_b32 v138, v137, v136, v250
	v_add_co_u32_e32 v136, vcc, 0x44000, v132
	s_waitcnt lgkmcnt(0)
	s_nop 0
	v_addc_co_u32_e32 v137, vcc, 0, v133, vcc
	global_store_dword v[136:137], v138, off offset:512
	s_nop 1
	v_mov_b32_dpp v136, v135 quad_perm:[1,0,3,2] row_mask:0xf bank_mask:0xf
	v_perm_b32 v137, v136, v135, v250
	v_add_co_u32_e32 v132, vcc, 0x66000, v132
	s_nop 1
	v_addc_co_u32_e32 v133, vcc, 0, v133, vcc
	global_store_dword v[132:133], v137, off offset:768
	v_cvt_pk_bf16_f32 v133, v100, v101
	s_nop 1
	v_mov_b32_dpp v138, v133 quad_perm:[1,0,3,2] row_mask:0xf bank_mask:0xf
	v_cvt_pk_bf16_f32 v132, v102, v103
	s_waitcnt lgkmcnt(0)
	v_cvt_pk_bf16_f32 v136, v96, v97
	v_cvt_pk_bf16_f32 v135, v98, v99
	v_perm_b32 v137, v138, v133, v250
	s_nop 1
	v_mov_b32_dpp v133, v132 quad_perm:[1,0,3,2] row_mask:0xf bank_mask:0xf
	global_store_dword v[130:131], v137, off offset:32
	v_perm_b32 v137, v133, v132, v250
	s_waitcnt lgkmcnt(0)
	v_lshl_add_u64 v[132:133], v[130:131], 0, 32
	v_add_co_u32_e32 v138, vcc, 0x22000, v132
	s_nop 1
	v_addc_co_u32_e32 v139, vcc, 0, v133, vcc
	global_store_dword v[138:139], v137, off offset:256
	s_nop 1
	v_mov_b32_dpp v137, v136 quad_perm:[1,0,3,2] row_mask:0xf bank_mask:0xf
	v_perm_b32 v138, v137, v136, v250
	v_add_co_u32_e32 v136, vcc, 0x44000, v132
	s_waitcnt lgkmcnt(0)
	s_nop 0
	v_addc_co_u32_e32 v137, vcc, 0, v133, vcc
	global_store_dword v[136:137], v138, off offset:512
	s_nop 1
	v_mov_b32_dpp v136, v135 quad_perm:[1,0,3,2] row_mask:0xf bank_mask:0xf
	v_perm_b32 v137, v136, v135, v250
	v_add_co_u32_e32 v132, vcc, 0x66000, v132
	s_nop 1
	v_addc_co_u32_e32 v133, vcc, 0, v133, vcc
	global_store_dword v[132:133], v137, off offset:768
	v_cvt_pk_bf16_f32 v133, v92, v93
	s_nop 1
	v_mov_b32_dpp v138, v133 quad_perm:[1,0,3,2] row_mask:0xf bank_mask:0xf
	v_cvt_pk_bf16_f32 v132, v94, v95
	s_waitcnt lgkmcnt(0)
	v_cvt_pk_bf16_f32 v136, v88, v89
	v_cvt_pk_bf16_f32 v135, v90, v91
	v_perm_b32 v137, v138, v133, v250
	s_nop 1
	v_mov_b32_dpp v133, v132 quad_perm:[1,0,3,2] row_mask:0xf bank_mask:0xf
	global_store_dword v[128:129], v137, off offset:64
	v_perm_b32 v137, v133, v132, v250
	s_waitcnt lgkmcnt(0)
; __device__ __forceinline__ unsigned cvt_pk_bf16(float lo, float hi) { unsigned r; asm volatile("v_cvt_pk_bf16_f32 %0, %1, %2" : "=v"(r) : "v"(lo), "v"(hi)); return r; }
;     __device__ __forceinline__ void operator()(const f32x4 (&acc)[2][2][4][2], const Unit& u, int wr, int wc, int fr, int fq) const {
;     ...
;         } else if (u.pn >= 12) {
;             const int odd = fr & 1;
; #pragma unroll
;             for (int ai = 0; ai < 2; ++ai)
; #pragma unroll
;                 for (int m = 0; m < 4; ++m) { const int tokrow = row0 + ai * HALF + m * 16;
; #pragma unroll
;                     for (int bj = 0; bj < 2; ++bj) {
;                         const f32x4 v0 = acc[ai][bj][m][0], v1 = acc[ai][bj][m][1];
;                         u32x4 w; w.x = cvt_pk_bf16(v0[0], v0[1]); w.y = cvt_pk_bf16(v0[2], v0[3]); w.z = cvt_pk_bf16(v1[0], v1[1]); w.w = cvt_pk_bf16(v1[2], v1[3]);
;                         bf16_t* vt = KT + (size_t)(512 + (u.pn - 12) * BM + bj * HALF + wc * 32 + 8 * fq + odd) * ldk + (tokrow - odd);
; #pragma unroll
;                         for (int q = 0; q < 4; ++q) { const unsigned mine = w[q], other = (unsigned)__shfl_xor((int)mine, 1);
;                             const unsigned pr = odd ? ((other >> 16) | (mine & 0xffff0000u)) : ((mine & 0xffffu) | (other << 16));
;                             *(unsigned*)(vt + (size_t)(2 * q) * ldk) = pr; }
;                     } }
	v_lshl_add_u64 v[132:133], v[128:129], 0, 64
	v_add_co_u32_e32 v138, vcc, 0x22000, v132
	s_nop 1
	v_addc_co_u32_e32 v139, vcc, 0, v133, vcc
	global_store_dword v[138:139], v137, off offset:256
	s_nop 1
	v_mov_b32_dpp v137, v136 quad_perm:[1,0,3,2] row_mask:0xf bank_mask:0xf
	v_perm_b32 v138, v137, v136, v250
	v_add_co_u32_e32 v136, vcc, 0x44000, v132
	s_waitcnt lgkmcnt(0)
	s_nop 0
	v_addc_co_u32_e32 v137, vcc, 0, v133, vcc
	global_store_dword v[136:137], v138, off offset:512
	s_nop 1
	v_mov_b32_dpp v136, v135 quad_perm:[1,0,3,2] row_mask:0xf bank_mask:0xf
	v_perm_b32 v137, v136, v135, v250
	v_add_co_u32_e32 v132, vcc, 0x66000, v132
	s_nop 1
	v_addc_co_u32_e32 v133, vcc, 0, v133, vcc
	global_store_dword v[132:133], v137, off offset:768
	v_cvt_pk_bf16_f32 v133, v84, v85
	s_nop 1
	v_mov_b32_dpp v138, v133 quad_perm:[1,0,3,2] row_mask:0xf bank_mask:0xf
	v_cvt_pk_bf16_f32 v132, v86, v87
	s_waitcnt lgkmcnt(0)
	v_cvt_pk_bf16_f32 v136, v80, v81
	v_cvt_pk_bf16_f32 v135, v82, v83
	v_perm_b32 v137, v138, v133, v250
	s_nop 1
	v_mov_b32_dpp v133, v132 quad_perm:[1,0,3,2] row_mask:0xf bank_mask:0xf
	global_store_dword v[130:131], v137, off offset:64
	v_perm_b32 v137, v133, v132, v250
	s_waitcnt lgkmcnt(0)
	v_lshl_add_u64 v[132:133], v[130:131], 0, 64
	v_add_co_u32_e32 v138, vcc, 0x22000, v132
	s_nop 1
	v_addc_co_u32_e32 v139, vcc, 0, v133, vcc
	global_store_dword v[138:139], v137, off offset:256
	s_nop 1
	v_mov_b32_dpp v137, v136 quad_perm:[1,0,3,2] row_mask:0xf bank_mask:0xf
	v_perm_b32 v138, v137, v136, v250
	v_add_co_u32_e32 v136, vcc, 0x44000, v132
	s_waitcnt lgkmcnt(0)
	s_nop 0
	v_addc_co_u32_e32 v137, vcc, 0, v133, vcc
	global_store_dword v[136:137], v138, off offset:512
	s_nop 1
	v_mov_b32_dpp v136, v135 quad_perm:[1,0,3,2] row_mask:0xf bank_mask:0xf
	v_perm_b32 v137, v136, v135, v250
	v_add_co_u32_e32 v132, vcc, 0x66000, v132
	s_nop 1
	v_addc_co_u32_e32 v133, vcc, 0, v133, vcc
	global_store_dword v[132:133], v137, off offset:768
	v_cvt_pk_bf16_f32 v133, v76, v77
	s_nop 1
	v_mov_b32_dpp v138, v133 quad_perm:[1,0,3,2] row_mask:0xf bank_mask:0xf
	v_cvt_pk_bf16_f32 v132, v78, v79
	s_waitcnt lgkmcnt(0)
	v_cvt_pk_bf16_f32 v136, v72, v73
	v_cvt_pk_bf16_f32 v135, v74, v75
	v_perm_b32 v137, v138, v133, v250
	s_nop 1
	v_mov_b32_dpp v133, v132 quad_perm:[1,0,3,2] row_mask:0xf bank_mask:0xf
	global_store_dword v[128:129], v137, off offset:96
	v_perm_b32 v137, v133, v132, v250
	s_waitcnt lgkmcnt(0)
	v_lshl_add_u64 v[132:133], v[128:129], 0, s[36:37]
	v_add_co_u32_e32 v138, vcc, 0x22000, v132
	s_nop 1
	v_addc_co_u32_e32 v139, vcc, 0, v133, vcc
	global_store_dword v[138:139], v137, off offset:256
	s_nop 1
	v_mov_b32_dpp v137, v136 quad_perm:[1,0,3,2] row_mask:0xf bank_mask:0xf
	v_perm_b32 v138, v137, v136, v250
	v_add_co_u32_e32 v136, vcc, 0x44000, v132
	s_waitcnt lgkmcnt(0)
	s_nop 0
	v_addc_co_u32_e32 v137, vcc, 0, v133, vcc
	global_store_dword v[136:137], v138, off offset:512
	s_nop 1
	v_mov_b32_dpp v136, v135 quad_perm:[1,0,3,2] row_mask:0xf bank_mask:0xf
	v_perm_b32 v137, v136, v135, v250
	v_add_co_u32_e32 v132, vcc, 0x66000, v132
	s_nop 1
	v_addc_co_u32_e32 v133, vcc, 0, v133, vcc
	global_store_dword v[132:133], v137, off offset:768
	v_cvt_pk_bf16_f32 v133, v68, v69
	s_nop 1
	v_mov_b32_dpp v138, v133 quad_perm:[1,0,3,2] row_mask:0xf bank_mask:0xf
	v_cvt_pk_bf16_f32 v132, v70, v71
	s_waitcnt lgkmcnt(0)
	v_cvt_pk_bf16_f32 v136, v64, v65
	v_cvt_pk_bf16_f32 v135, v66, v67
	v_perm_b32 v137, v138, v133, v250
	s_nop 1
	v_mov_b32_dpp v133, v132 quad_perm:[1,0,3,2] row_mask:0xf bank_mask:0xf
	global_store_dword v[130:131], v137, off offset:96
	v_perm_b32 v137, v133, v132, v250
	s_waitcnt lgkmcnt(0)
	v_lshl_add_u64 v[132:133], v[130:131], 0, s[36:37]
	v_add_co_u32_e32 v138, vcc, 0x22000, v132
	s_nop 1
	v_addc_co_u32_e32 v139, vcc, 0, v133, vcc
	global_store_dword v[138:139], v137, off offset:256
	s_nop 1
	v_mov_b32_dpp v137, v136 quad_perm:[1,0,3,2] row_mask:0xf bank_mask:0xf
	v_perm_b32 v138, v137, v136, v250
	v_add_co_u32_e32 v136, vcc, 0x44000, v132
	s_waitcnt lgkmcnt(0)
	s_nop 0
	v_addc_co_u32_e32 v137, vcc, 0, v133, vcc
	global_store_dword v[136:137], v138, off offset:512
	s_nop 1
	v_mov_b32_dpp v136, v135 quad_perm:[1,0,3,2] row_mask:0xf bank_mask:0xf
	v_perm_b32 v137, v136, v135, v250
	v_add_co_u32_e32 v132, vcc, 0x66000, v132
	s_nop 1
	v_addc_co_u32_e32 v133, vcc, 0, v133, vcc
	global_store_dword v[132:133], v137, off offset:768
	v_cvt_pk_bf16_f32 v133, v60, v61
	s_nop 1
	v_mov_b32_dpp v138, v133 quad_perm:[1,0,3,2] row_mask:0xf bank_mask:0xf
	v_cvt_pk_bf16_f32 v132, v62, v63
	s_waitcnt lgkmcnt(0)
	v_cvt_pk_bf16_f32 v136, v56, v57
	v_cvt_pk_bf16_f32 v135, v58, v59
	v_perm_b32 v137, v138, v133, v250
	s_nop 1
	v_mov_b32_dpp v133, v132 quad_perm:[1,0,3,2] row_mask:0xf bank_mask:0xf
	global_store_dword v[128:129], v137, off offset:256
	v_perm_b32 v137, v133, v132, v250
	s_mov_b64 s[16:17], 0x100
	s_waitcnt lgkmcnt(0)
	v_lshl_add_u64 v[132:133], v[128:129], 0, s[16:17]
	v_add_co_u32_e32 v138, vcc, 0x22000, v132
	s_nop 1
	v_addc_co_u32_e32 v139, vcc, 0, v133, vcc
	global_store_dword v[138:139], v137, off offset:256
	s_nop 1
	v_mov_b32_dpp v137, v136 quad_perm:[1,0,3,2] row_mask:0xf bank_mask:0xf
	v_perm_b32 v138, v137, v136, v250
	v_add_co_u32_e32 v136, vcc, 0x44000, v132
	s_waitcnt lgkmcnt(0)
	s_nop 0
	v_addc_co_u32_e32 v137, vcc, 0, v133, vcc
	global_store_dword v[136:137], v138, off offset:512
	s_nop 1
	v_mov_b32_dpp v136, v135 quad_perm:[1,0,3,2] row_mask:0xf bank_mask:0xf
	v_perm_b32 v137, v136, v135, v250
	v_add_co_u32_e32 v132, vcc, 0x66000, v132
	s_nop 1
	v_addc_co_u32_e32 v133, vcc, 0, v133, vcc
	global_store_dword v[132:133], v137, off offset:768
	v_cvt_pk_bf16_f32 v133, v52, v53
	s_nop 1
	v_mov_b32_dpp v138, v133 quad_perm:[1,0,3,2] row_mask:0xf bank_mask:0xf
	v_cvt_pk_bf16_f32 v132, v54, v55
	s_waitcnt lgkmcnt(0)
; __device__ __forceinline__ unsigned cvt_pk_bf16(float lo, float hi) { unsigned r; asm volatile("v_cvt_pk_bf16_f32 %0, %1, %2" : "=v"(r) : "v"(lo), "v"(hi)); return r; }
;     __device__ __forceinline__ void operator()(const f32x4 (&acc)[2][2][4][2], const Unit& u, int wr, int wc, int fr, int fq) const {
;     ...
;         } else if (u.pn >= 12) {
;             const int odd = fr & 1;
; #pragma unroll
;             for (int ai = 0; ai < 2; ++ai)
; #pragma unroll
;                 for (int m = 0; m < 4; ++m) { const int tokrow = row0 + ai * HALF + m * 16;
; #pragma unroll
;                     for (int bj = 0; bj < 2; ++bj) {
;                         const f32x4 v0 = acc[ai][bj][m][0], v1 = acc[ai][bj][m][1];
;                         u32x4 w; w.x = cvt_pk_bf16(v0[0], v0[1]); w.y = cvt_pk_bf16(v0[2], v0[3]); w.z = cvt_pk_bf16(v1[0], v1[1]); w.w = cvt_pk_bf16(v1[2], v1[3]);
;                         bf16_t* vt = KT + (size_t)(512 + (u.pn - 12) * BM + bj * HALF + wc * 32 + 8 * fq + odd) * ldk + (tokrow - odd);
; #pragma unroll
;                         for (int q = 0; q < 4; ++q) { const unsigned mine = w[q], other = (unsigned)__shfl_xor((int)mine, 1);
;                             const unsigned pr = odd ? ((other >> 16) | (mine & 0xffff0000u)) : ((mine & 0xffffu) | (other << 16));
;                             *(unsigned*)(vt + (size_t)(2 * q) * ldk) = pr; }
;                     } }
	v_cvt_pk_bf16_f32 v136, v48, v49
	v_cvt_pk_bf16_f32 v135, v50, v51
	v_perm_b32 v137, v138, v133, v250
	s_nop 1
	v_mov_b32_dpp v133, v132 quad_perm:[1,0,3,2] row_mask:0xf bank_mask:0xf
	global_store_dword v[130:131], v137, off offset:256
	v_perm_b32 v137, v133, v132, v250
	s_mov_b64 s[16:17], 0x100
	s_waitcnt lgkmcnt(0)
	v_lshl_add_u64 v[132:133], v[130:131], 0, s[16:17]
	v_add_co_u32_e32 v138, vcc, 0x22000, v132
	s_nop 1
	v_addc_co_u32_e32 v139, vcc, 0, v133, vcc
	global_store_dword v[138:139], v137, off offset:256
	s_nop 1
	v_mov_b32_dpp v137, v136 quad_perm:[1,0,3,2] row_mask:0xf bank_mask:0xf
	v_perm_b32 v138, v137, v136, v250
	v_add_co_u32_e32 v136, vcc, 0x44000, v132
	s_waitcnt lgkmcnt(0)
	s_nop 0
	v_addc_co_u32_e32 v137, vcc, 0, v133, vcc
	global_store_dword v[136:137], v138, off offset:512
	s_nop 1
	v_mov_b32_dpp v136, v135 quad_perm:[1,0,3,2] row_mask:0xf bank_mask:0xf
	v_perm_b32 v137, v136, v135, v250
	v_add_co_u32_e32 v132, vcc, 0x66000, v132
	s_nop 1
	v_addc_co_u32_e32 v133, vcc, 0, v133, vcc
	global_store_dword v[132:133], v137, off offset:768
	v_cvt_pk_bf16_f32 v133, v44, v45
	s_nop 1
	v_mov_b32_dpp v138, v133 quad_perm:[1,0,3,2] row_mask:0xf bank_mask:0xf
	v_cvt_pk_bf16_f32 v132, v46, v47
	s_waitcnt lgkmcnt(0)
	v_cvt_pk_bf16_f32 v136, v40, v41
	v_cvt_pk_bf16_f32 v135, v42, v43
	v_perm_b32 v137, v138, v133, v250
	s_nop 1
	v_mov_b32_dpp v133, v132 quad_perm:[1,0,3,2] row_mask:0xf bank_mask:0xf
	global_store_dword v[128:129], v137, off offset:288
	v_perm_b32 v137, v133, v132, v250
	s_waitcnt lgkmcnt(0)
	v_lshl_add_u64 v[132:133], v[128:129], 0, s[38:39]
	v_add_co_u32_e32 v138, vcc, 0x22000, v132
	s_nop 1
	v_addc_co_u32_e32 v139, vcc, 0, v133, vcc
	global_store_dword v[138:139], v137, off offset:256
	s_nop 1
	v_mov_b32_dpp v137, v136 quad_perm:[1,0,3,2] row_mask:0xf bank_mask:0xf
	v_perm_b32 v138, v137, v136, v250
	v_add_co_u32_e32 v136, vcc, 0x44000, v132
	s_waitcnt lgkmcnt(0)
	s_nop 0
	v_addc_co_u32_e32 v137, vcc, 0, v133, vcc
	global_store_dword v[136:137], v138, off offset:512
	s_nop 1
	v_mov_b32_dpp v136, v135 quad_perm:[1,0,3,2] row_mask:0xf bank_mask:0xf
	v_perm_b32 v137, v136, v135, v250
	v_add_co_u32_e32 v132, vcc, 0x66000, v132
	s_nop 1
	v_addc_co_u32_e32 v133, vcc, 0, v133, vcc
	global_store_dword v[132:133], v137, off offset:768
	v_cvt_pk_bf16_f32 v133, v36, v37
	s_nop 1
	v_mov_b32_dpp v138, v133 quad_perm:[1,0,3,2] row_mask:0xf bank_mask:0xf
	v_cvt_pk_bf16_f32 v132, v38, v39
	s_waitcnt lgkmcnt(0)
	v_cvt_pk_bf16_f32 v136, v32, v33
	v_cvt_pk_bf16_f32 v135, v34, v35
	v_perm_b32 v137, v138, v133, v250
	s_nop 1
	v_mov_b32_dpp v133, v132 quad_perm:[1,0,3,2] row_mask:0xf bank_mask:0xf
	global_store_dword v[130:131], v137, off offset:288
	v_perm_b32 v137, v133, v132, v250
	s_waitcnt lgkmcnt(0)
	v_lshl_add_u64 v[132:133], v[130:131], 0, s[38:39]
	v_add_co_u32_e32 v138, vcc, 0x22000, v132
	s_nop 1
	v_addc_co_u32_e32 v139, vcc, 0, v133, vcc
	global_store_dword v[138:139], v137, off offset:256
	s_nop 1
	v_mov_b32_dpp v137, v136 quad_perm:[1,0,3,2] row_mask:0xf bank_mask:0xf
	v_perm_b32 v138, v137, v136, v250
	v_add_co_u32_e32 v136, vcc, 0x44000, v132
	s_waitcnt lgkmcnt(0)
	s_nop 0
	v_addc_co_u32_e32 v137, vcc, 0, v133, vcc
	global_store_dword v[136:137], v138, off offset:512
	s_nop 1
	v_mov_b32_dpp v136, v135 quad_perm:[1,0,3,2] row_mask:0xf bank_mask:0xf
	v_perm_b32 v137, v136, v135, v250
	v_add_co_u32_e32 v132, vcc, 0x66000, v132
	s_nop 1
	v_addc_co_u32_e32 v133, vcc, 0, v133, vcc
	global_store_dword v[132:133], v137, off offset:768
	v_cvt_pk_bf16_f32 v133, v28, v29
	s_nop 1
	v_mov_b32_dpp v138, v133 quad_perm:[1,0,3,2] row_mask:0xf bank_mask:0xf
	v_cvt_pk_bf16_f32 v132, v30, v31
	s_waitcnt lgkmcnt(0)
	v_cvt_pk_bf16_f32 v136, v24, v25
	v_cvt_pk_bf16_f32 v135, v26, v27
	v_perm_b32 v137, v138, v133, v250
	s_nop 1
	v_mov_b32_dpp v133, v132 quad_perm:[1,0,3,2] row_mask:0xf bank_mask:0xf
	global_store_dword v[128:129], v137, off offset:320
	v_perm_b32 v137, v133, v132, v250
	s_waitcnt lgkmcnt(0)
	v_lshl_add_u64 v[132:133], v[128:129], 0, s[40:41]
	v_add_co_u32_e32 v138, vcc, 0x22000, v132
	s_nop 1
	v_addc_co_u32_e32 v139, vcc, 0, v133, vcc
	global_store_dword v[138:139], v137, off offset:256
	s_nop 1
	v_mov_b32_dpp v137, v136 quad_perm:[1,0,3,2] row_mask:0xf bank_mask:0xf
	v_perm_b32 v138, v137, v136, v250
	v_add_co_u32_e32 v136, vcc, 0x44000, v132
	s_waitcnt lgkmcnt(0)
; __device__ __forceinline__ unsigned cvt_pk_bf16(float lo, float hi) { unsigned r; asm volatile("v_cvt_pk_bf16_f32 %0, %1, %2" : "=v"(r) : "v"(lo), "v"(hi)); return r; }
;     __device__ __forceinline__ void operator()(const f32x4 (&acc)[2][2][4][2], const Unit& u, int wr, int wc, int fr, int fq) const {
;     ...
;         } else if (u.pn >= 12) {
;             const int odd = fr & 1;
; #pragma unroll
;             for (int ai = 0; ai < 2; ++ai)
; #pragma unroll
;                 for (int m = 0; m < 4; ++m) { const int tokrow = row0 + ai * HALF + m * 16;
; #pragma unroll
;                     for (int bj = 0; bj < 2; ++bj) {
;                         const f32x4 v0 = acc[ai][bj][m][0], v1 = acc[ai][bj][m][1];
;                         u32x4 w; w.x = cvt_pk_bf16(v0[0], v0[1]); w.y = cvt_pk_bf16(v0[2], v0[3]); w.z = cvt_pk_bf16(v1[0], v1[1]); w.w = cvt_pk_bf16(v1[2], v1[3]);
;                         bf16_t* vt = KT + (size_t)(512 + (u.pn - 12) * BM + bj * HALF + wc * 32 + 8 * fq + odd) * ldk + (tokrow - odd);
; #pragma unroll
;                         for (int q = 0; q < 4; ++q) { const unsigned mine = w[q], other = (unsigned)__shfl_xor((int)mine, 1);
;                             const unsigned pr = odd ? ((other >> 16) | (mine & 0xffff0000u)) : ((mine & 0xffffu) | (other << 16));
;                             *(unsigned*)(vt + (size_t)(2 * q) * ldk) = pr; }
;                     } }
	s_nop 0
	v_addc_co_u32_e32 v137, vcc, 0, v133, vcc
	global_store_dword v[136:137], v138, off offset:512
	s_nop 1
	v_mov_b32_dpp v136, v135 quad_perm:[1,0,3,2] row_mask:0xf bank_mask:0xf
	v_perm_b32 v137, v136, v135, v250
	v_add_co_u32_e32 v132, vcc, 0x66000, v132
	s_nop 1
	v_addc_co_u32_e32 v133, vcc, 0, v133, vcc
	global_store_dword v[132:133], v137, off offset:768
	v_cvt_pk_bf16_f32 v133, v20, v21
	s_nop 1
	v_mov_b32_dpp v138, v133 quad_perm:[1,0,3,2] row_mask:0xf bank_mask:0xf
	v_cvt_pk_bf16_f32 v132, v22, v23
	s_waitcnt lgkmcnt(0)
	v_cvt_pk_bf16_f32 v136, v16, v17
	v_cvt_pk_bf16_f32 v135, v18, v19
	v_perm_b32 v137, v138, v133, v250
	s_nop 1
	v_mov_b32_dpp v133, v132 quad_perm:[1,0,3,2] row_mask:0xf bank_mask:0xf
	global_store_dword v[130:131], v137, off offset:320
	v_perm_b32 v137, v133, v132, v250
	s_waitcnt lgkmcnt(0)
	v_lshl_add_u64 v[132:133], v[130:131], 0, s[40:41]
	v_add_co_u32_e32 v138, vcc, 0x22000, v132
	s_nop 1
	v_addc_co_u32_e32 v139, vcc, 0, v133, vcc
	global_store_dword v[138:139], v137, off offset:256
	s_nop 1
	v_mov_b32_dpp v137, v136 quad_perm:[1,0,3,2] row_mask:0xf bank_mask:0xf
	v_perm_b32 v138, v137, v136, v250
	v_add_co_u32_e32 v136, vcc, 0x44000, v132
	s_waitcnt lgkmcnt(0)
	s_nop 0
	v_addc_co_u32_e32 v137, vcc, 0, v133, vcc
	global_store_dword v[136:137], v138, off offset:512
	s_nop 1
	v_mov_b32_dpp v136, v135 quad_perm:[1,0,3,2] row_mask:0xf bank_mask:0xf
	v_perm_b32 v137, v136, v135, v250
	v_add_co_u32_e32 v132, vcc, 0x66000, v132
	s_nop 1
	v_addc_co_u32_e32 v133, vcc, 0, v133, vcc
	global_store_dword v[132:133], v137, off offset:768
	s_waitcnt lgkmcnt(0)
	v_cvt_pk_bf16_f32 v136, v12, v13
	s_nop 1
	v_mov_b32_dpp v138, v136 quad_perm:[1,0,3,2] row_mask:0xf bank_mask:0xf
	v_cvt_pk_bf16_f32 v135, v14, v15
	v_cvt_pk_bf16_f32 v133, v8, v9
	v_cvt_pk_bf16_f32 v132, v10, v11
	v_perm_b32 v137, v138, v136, v250
	s_waitcnt lgkmcnt(0)
	s_nop 1
	v_mov_b32_dpp v138, v135 quad_perm:[1,0,3,2] row_mask:0xf bank_mask:0xf
	global_store_dword v[128:129], v137, off offset:352
	v_perm_b32 v136, v138, v135, v250
	s_nop 1
	v_mov_b32_dpp v135, v133 quad_perm:[1,0,3,2] row_mask:0xf bank_mask:0xf
	v_lshl_add_u64 v[128:129], v[128:129], 0, s[42:43]
	s_waitcnt lgkmcnt(0)
	v_add_co_u32_e32 v138, vcc, 0x22000, v128
	s_nop 1
	v_addc_co_u32_e32 v139, vcc, 0, v129, vcc
	global_store_dword v[138:139], v136, off offset:256
	v_perm_b32 v136, v135, v133, v250
	s_nop 1
	v_mov_b32_dpp v133, v132 quad_perm:[1,0,3,2] row_mask:0xf bank_mask:0xf
	v_add_co_u32_e32 v138, vcc, 0x44000, v128
	s_nop 1
	v_addc_co_u32_e32 v139, vcc, 0, v129, vcc
	global_store_dword v[138:139], v136, off offset:512
	v_perm_b32 v135, v133, v132, v250
	v_add_co_u32_e32 v128, vcc, 0x66000, v128
	s_nop 1
	v_addc_co_u32_e32 v129, vcc, 0, v129, vcc
	global_store_dword v[128:129], v135, off offset:768
	v_cvt_pk_bf16_f32 v129, v4, v5
	s_nop 1
	v_mov_b32_dpp v136, v129 quad_perm:[1,0,3,2] row_mask:0xf bank_mask:0xf
	v_cvt_pk_bf16_f32 v128, v6, v7
	s_waitcnt lgkmcnt(0)
	v_cvt_pk_bf16_f32 v133, v0, v1
	v_cvt_pk_bf16_f32 v132, v2, v3
	v_perm_b32 v135, v136, v129, v250
	s_nop 1
	v_mov_b32_dpp v129, v128 quad_perm:[1,0,3,2] row_mask:0xf bank_mask:0xf
	global_store_dword v[130:131], v135, off offset:352
	v_perm_b32 v135, v129, v128, v250
	s_waitcnt lgkmcnt(0)
	v_lshl_add_u64 v[128:129], v[130:131], 0, s[42:43]
	v_add_co_u32_e32 v130, vcc, 0x22000, v128
	s_nop 1
	v_addc_co_u32_e32 v131, vcc, 0, v129, vcc
	global_store_dword v[130:131], v135, off offset:256
	s_nop 1
	v_mov_b32_dpp v131, v133 quad_perm:[1,0,3,2] row_mask:0xf bank_mask:0xf
	v_perm_b32 v130, v131, v133, v250
	s_waitcnt lgkmcnt(0)
	s_nop 1
	v_mov_b32_dpp v131, v132 quad_perm:[1,0,3,2] row_mask:0xf bank_mask:0xf
	v_add_co_u32_e32 v136, vcc, 0x44000, v128
	s_nop 1
	v_addc_co_u32_e32 v137, vcc, 0, v129, vcc
	global_store_dword v[136:137], v130, off offset:512
	v_perm_b32 v130, v131, v132, v250
	v_add_co_u32_e32 v128, vcc, 0x66000, v128
	s_nop 1
	v_addc_co_u32_e32 v129, vcc, 0, v129, vcc
	global_store_dword v[128:129], v130, off offset:768

; __device__ __forceinline__ unsigned cvt_pk_bf16(float lo, float hi) { unsigned r; asm volatile("v_cvt_pk_bf16_f32 %0, %1, %2" : "=v"(r) : "v"(lo), "v"(hi)); return r; }
;     __device__ __forceinline__ void operator()(const f32x4 (&acc)[2][2][4][2], const Unit& u, int wr, int wc, int fr, int fq) const {
;     ...
;                 for (int m = 0; m < 4; ++m) { const int row = row0 + ai * HALF + m * 16, t = row & 4095, p = t & 127;
;                     c4[m] = *(const f32x4*)(cs + t * 64 + 16 * wc + 4 * fq); s4[m] = *(const f32x4*)(sn + t * 64 + 16 * wc + 4 * fq);
;                     sc[m][0] = dtab[hb * 128 + p]; sc[m][1] = dtab[(hb + 1) * 128 + p]; }
;                 __builtin_amdgcn_sched_barrier(0);
; #pragma unroll
;                 for (int m = 0; m < 4; ++m) { bf16_t* rowp = O + (size_t)(row0 + ai * HALF + m * 16) * 3072 + col0;
; #pragma unroll
;                     for (int bj = 0; bj < 2; ++bj) {
;                         const float s_ = sc[m][bj]; const f32x4 cc = c4[m], ss = s4[m];
;                         const f32x4 v0 = acc[ai][bj][m][0], v1 = acc[ai][bj][m][1];
;                         u32x4 w;
;                         w.x = cvt_pk_bf16((v0[0] * cc[0] - v0[1] * ss[0]) * s_, (v0[0] * ss[0] + v0[1] * cc[0]) * s_);
;                         w.y = cvt_pk_bf16((v0[2] * cc[1] - v0[3] * ss[1]) * s_, (v0[2] * ss[1] + v0[3] * cc[1]) * s_);
;                         w.z = cvt_pk_bf16((v1[0] * cc[2] - v1[1] * ss[2]) * s_, (v1[0] * ss[2] + v1[1] * cc[2]) * s_);
;                         w.w = cvt_pk_bf16((v1[2] * cc[3] - v1[3] * ss[3]) * s_, (v1[2] * ss[3] + v1[3] * cc[3]) * s_);
;                         *(u32x4*)(rowp + bj * HALF) = w;
;                         if (u.pn >= 8) {
;                             const int tokrow = row0 + ai * HALF + m * 16, odd = fr & 1;
;                             bf16_t* kt = KT + (size_t)((hb + bj) * 128 + wc * 32 + 8 * fq + odd) * ldk + (tokrow - odd);
; #pragma unroll
;                             for (int q = 0; q < 4; ++q) { const unsigned mine = w[q], other = (unsigned)__shfl_xor((int)mine, 1);
;                                 const unsigned pr = odd ? ((other >> 16) | (mine & 0xffff0000u)) : ((mine & 0xffffu) | (other << 16));
;                                 *(unsigned*)(kt + (size_t)(2 * q) * ldk) = pr; }
;                         }
.LBB0_535:
	s_cmp_gt_i32 s6, 7
	s_cselect_b64 s[80:81], -1, 0
	s_and_b64 s[16:17], s[80:81], exec
	s_mov_b32 s16, 0x581000
	s_cselect_b32 s16, s16, 0x580000
	v_and_b32_e32 v132, 0xfcf, v210
	s_add_u32 s78, s86, s16
	v_lshlrev_b32_e32 v128, 8, v132
	v_mov_b32_e32 v129, v163
	s_addc_u32 s79, s87, 0
	s_and_b32 s71, s7, 0x100
	s_waitcnt lgkmcnt(0)
	v_lshl_add_u64 v[130:131], v[178:179], 0, v[128:129]
	v_lshl_add_u64 v[128:129], v[180:181], 0, v[128:129]
	global_load_dwordx4 v[152:155], v[130:131], off
	global_load_dwordx4 v[156:159], v[128:129], off
	v_or_b32_e32 v128, s71, v208
	v_lshlrev_b32_e32 v186, 2, v128
	v_or_b32_e32 v128, 16, v132
	s_movk_i32 s7, 0x5f
	v_lshlrev_b32_e32 v128, 8, v128
	v_mov_b32_e32 v129, v163
	v_bitop3_b32 v133, v132, s7, 16 bitop3:0xc8
	v_lshl_add_u64 v[130:131], v[178:179], 0, v[128:129]
	v_lshl_add_u64 v[128:129], v[180:181], 0, v[128:129]
	global_load_dwordx4 v[144:147], v[130:131], off
	global_load_dwordx4 v[148:151], v[128:129], off
	v_or_b32_e32 v128, s71, v133
	v_lshlrev_b32_e32 v128, 2, v128
	global_load_dword v215, v128, s[78:79]
	global_load_dword v214, v128, s[78:79] offset:512
	v_or_b32_e32 v128, 32, v132
	s_movk_i32 s7, 0x6f
	v_lshlrev_b32_e32 v128, 8, v128
	v_mov_b32_e32 v129, v163
	v_bitop3_b32 v133, v132, s7, 32 bitop3:0xc8
	v_lshl_add_u64 v[130:131], v[178:179], 0, v[128:129]
	v_lshl_add_u64 v[128:129], v[180:181], 0, v[128:129]
	global_load_dwordx4 v[136:139], v[130:131], off
	global_load_dwordx4 v[140:143], v[128:129], off
	v_or_b32_e32 v128, s71, v133
	v_lshlrev_b32_e32 v128, 2, v128
	s_movk_i32 s7, 0x7f
	global_load_dword v213, v128, s[78:79]
	global_load_dword v212, v128, s[78:79] offset:512
	v_or_b32_e32 v128, 48, v132
	v_bitop3_b32 v187, v132, s7, 48 bitop3:0xc8
	v_lshlrev_b32_e32 v128, 8, v128
	v_mov_b32_e32 v129, v163
	v_or_b32_e32 v187, s71, v187
	v_lshl_add_u64 v[130:131], v[178:179], 0, v[128:129]
	v_lshl_add_u64 v[132:133], v[180:181], 0, v[128:129]
	v_lshlrev_b32_e32 v187, 2, v187
	global_load_dwordx4 v[128:131], v[130:131], off
	s_nop 0
	global_load_dwordx4 v[132:135], v[132:133], off
	s_nop 0
	global_load_dword v217, v186, s[78:79]
	global_load_dword v216, v186, s[78:79] offset:512
	global_load_dword v211, v187, s[78:79]
	s_nop 0
	global_load_dword v187, v187, s[78:79] offset:512
	s_cmp_lt_i32 s6, 8
	s_waitcnt vmcnt(0)
	v_mov_b32_e32 v192, v152
	v_mov_b32_e32 v193, v156
	v_pk_mul_f32 v[194:195], v[124:125], v[192:193]
	v_mov_b32_e32 v198, v158
	v_sub_f32_e32 v194, v194, v195
	v_mul_f32_e32 v196, v217, v194
	v_mov_b32_e32 v194, v156
	v_mov_b32_e32 v195, v152
	v_pk_mul_f32 v[124:125], v[124:125], v[194:195]
	v_mov_b32_e32 v156, v153
	v_add_f32_e32 v124, v125, v124
	v_mul_f32_e32 v124, v217, v124
	v_mov_b32_e32 v152, v157
	v_cvt_pk_bf16_f32 v124, v196, v124
	v_pk_mul_f32 v[196:197], v[126:127], v[156:157]
	v_pk_mul_f32 v[126:127], v[126:127], v[152:153]
	v_sub_f32_e32 v125, v196, v197
	v_add_f32_e32 v126, v127, v126
	v_mul_f32_e32 v125, v217, v125
	v_mul_f32_e32 v126, v217, v126
	v_mov_b32_e32 v196, v154
	v_mov_b32_e32 v197, v158
	v_mov_b32_e32 v199, v154
	v_cvt_pk_bf16_f32 v125, v125, v126
	v_pk_mul_f32 v[126:127], v[120:121], v[196:197]
	v_pk_mul_f32 v[120:121], v[120:121], v[198:199]
	v_sub_f32_e32 v126, v126, v127
	v_add_f32_e32 v120, v121, v120
	v_mul_f32_e32 v126, v217, v126
	v_mul_f32_e32 v120, v217, v120
	v_mov_b32_e32 v158, v155
	v_mov_b64_e32 v[188:189], s[64:65]
	v_cvt_pk_bf16_f32 v126, v126, v120
	v_pk_mul_f32 v[120:121], v[122:123], v[158:159]
	v_mad_i64_i32 v[188:189], s[6:7], v210, s47, v[188:189]
	v_sub_f32_e32 v120, v120, v121
	v_mov_b32_e32 v154, v159
	v_lshl_add_u64 v[190:191], v[162:163], 1, v[188:189]
	v_sub_u32_e32 v188, v210, v176
	v_mul_f32_e32 v127, v217, v120
	v_pk_mul_f32 v[120:121], v[122:123], v[154:155]
	v_ashrrev_i32_e32 v189, 31, v188
	v_add_f32_e32 v120, v121, v120
	v_mul_f32_e32 v120, v217, v120
	v_cvt_pk_bf16_f32 v127, v127, v120
	global_store_dwordx4 v[190:191], v[124:127], off
	s_cbranch_scc1 .LBB0_553
	v_cmp_lt_i32_e32 vcc, v228, v222
	s_nop 1
	v_cndmask_b32_e32 v120, v221, v228, vcc
	v_lshlrev_b32_e32 v122, 2, v120
	s_nop 1
	v_mov_b32_dpp v120, v124 quad_perm:[1,0,3,2] row_mask:0xf bank_mask:0xf
	v_perm_b32 v123, v120, v124, v250
	s_waitcnt lgkmcnt(0)
	v_or_b32_e32 v120, s71, v204
	v_mul_u32_u24_e32 v120, 0x8840, v120
	v_lshlrev_b32_e32 v120, 1, v120
	v_mov_b32_e32 v121, v163
	v_lshl_add_u64 v[120:121], s[66:67], 0, v[120:121]
	v_lshl_add_u64 v[120:121], v[188:189], 1, v[120:121]
	global_store_dword v[120:121], v123, off
	s_nop 1
	v_mov_b32_dpp v123, v125 quad_perm:[1,0,3,2] row_mask:0xf bank_mask:0xf
	v_perm_b32 v124, v123, v125, v250
	v_add_co_u32_e32 v224, vcc, 0x22000, v120
	s_nop 1
	v_addc_co_u32_e32 v225, vcc, 0, v121, vcc
	global_store_dword v[224:225], v124, off offset:256
	s_nop 1
	v_mov_b32_dpp v124, v126 quad_perm:[1,0,3,2] row_mask:0xf bank_mask:0xf
	v_perm_b32 v123, v124, v126, v250
	s_waitcnt lgkmcnt(0)
	s_nop 1
	v_mov_b32_dpp v124, v127 quad_perm:[1,0,3,2] row_mask:0xf bank_mask:0xf
	v_add_co_u32_e32 v224, vcc, 0x44000, v120
	s_nop 1
	v_addc_co_u32_e32 v225, vcc, 0, v121, vcc
	global_store_dword v[224:225], v123, off offset:512
	v_perm_b32 v122, v124, v127, v250
	v_add_co_u32_e32 v120, vcc, 0x66000, v120
	s_nop 1
	v_addc_co_u32_e32 v121, vcc, 0, v121, vcc
	global_store_dword v[120:121], v122, off offset:768
; __device__ __forceinline__ unsigned cvt_pk_bf16(float lo, float hi) { unsigned r; asm volatile("v_cvt_pk_bf16_f32 %0, %1, %2" : "=v"(r) : "v"(lo), "v"(hi)); return r; }
;     __device__ __forceinline__ void operator()(const f32x4 (&acc)[2][2][4][2], const Unit& u, int wr, int wc, int fr, int fq) const {
;     ...
;                 for (int m = 0; m < 4; ++m) { bf16_t* rowp = O + (size_t)(row0 + ai * HALF + m * 16) * 3072 + col0;
; #pragma unroll
;                     for (int bj = 0; bj < 2; ++bj) {
;                         const float s_ = sc[m][bj]; const f32x4 cc = c4[m], ss = s4[m];
;                         const f32x4 v0 = acc[ai][bj][m][0], v1 = acc[ai][bj][m][1];
;                         u32x4 w;
;                         w.x = cvt_pk_bf16((v0[0] * cc[0] - v0[1] * ss[0]) * s_, (v0[0] * ss[0] + v0[1] * cc[0]) * s_);
;                         w.y = cvt_pk_bf16((v0[2] * cc[1] - v0[3] * ss[1]) * s_, (v0[2] * ss[1] + v0[3] * cc[1]) * s_);
;                         w.z = cvt_pk_bf16((v1[0] * cc[2] - v1[1] * ss[2]) * s_, (v1[0] * ss[2] + v1[1] * cc[2]) * s_);
;                         w.w = cvt_pk_bf16((v1[2] * cc[3] - v1[3] * ss[3]) * s_, (v1[2] * ss[3] + v1[3] * cc[3]) * s_);
;                         *(u32x4*)(rowp + bj * HALF) = w;
;                         if (u.pn >= 8) {
;                             const int tokrow = row0 + ai * HALF + m * 16, odd = fr & 1;
;                             bf16_t* kt = KT + (size_t)((hb + bj) * 128 + wc * 32 + 8 * fq + odd) * ldk + (tokrow - odd);
; #pragma unroll
;                             for (int q = 0; q < 4; ++q) { const unsigned mine = w[q], other = (unsigned)__shfl_xor((int)mine, 1);
;                                 const unsigned pr = odd ? ((other >> 16) | (mine & 0xffff0000u)) : ((mine & 0xffffu) | (other << 16));
;                                 *(unsigned*)(kt + (size_t)(2 * q) * ldk) = pr; }
;                         }
.LBB0_553:
	v_pk_mul_f32 v[120:121], v[116:117], v[192:193]
	v_pk_mul_f32 v[116:117], v[116:117], v[194:195]
	v_sub_f32_e32 v120, v120, v121
	v_add_f32_e32 v116, v117, v116
	v_mul_f32_e32 v120, v216, v120
	v_mul_f32_e32 v116, v216, v116
	v_cvt_pk_bf16_f32 v116, v120, v116
	v_pk_mul_f32 v[120:121], v[118:119], v[156:157]
	v_pk_mul_f32 v[118:119], v[118:119], v[152:153]
	v_sub_f32_e32 v117, v120, v121
	v_add_f32_e32 v118, v119, v118
	v_mul_f32_e32 v117, v216, v117
	v_mul_f32_e32 v118, v216, v118
	v_cvt_pk_bf16_f32 v117, v117, v118
	v_pk_mul_f32 v[118:119], v[112:113], v[196:197]
	v_pk_mul_f32 v[112:113], v[112:113], v[198:199]
	v_sub_f32_e32 v118, v118, v119
	v_add_f32_e32 v112, v113, v112
	v_mul_f32_e32 v118, v216, v118
	v_mul_f32_e32 v112, v216, v112
	v_cvt_pk_bf16_f32 v118, v118, v112
	v_pk_mul_f32 v[112:113], v[114:115], v[158:159]
	s_andn2_b64 vcc, exec, s[80:81]
	v_sub_f32_e32 v112, v112, v113
	v_mul_f32_e32 v119, v216, v112
	v_pk_mul_f32 v[112:113], v[114:115], v[154:155]
	s_nop 0
	v_add_f32_e32 v112, v113, v112
	v_mul_f32_e32 v112, v216, v112
	v_cvt_pk_bf16_f32 v119, v119, v112
	v_cndmask_b32_e64 v112, 0, 1, s[80:81]
	v_cmp_ne_u32_e64 s[6:7], 1, v112
	global_store_dwordx4 v[190:191], v[116:119], off offset:256
	s_cbranch_vccnz .LBB0_571
	v_cmp_lt_i32_e32 vcc, v228, v222
	s_nop 1
	v_cndmask_b32_e32 v112, v221, v228, vcc
	v_lshlrev_b32_e32 v114, 2, v112
	s_nop 1
	v_mov_b32_dpp v112, v116 quad_perm:[1,0,3,2] row_mask:0xf bank_mask:0xf
	v_perm_b32 v115, v112, v116, v250
	s_waitcnt lgkmcnt(0)
	v_or_b32_e32 v112, s71, v207
	v_mul_u32_u24_e32 v112, 0x8840, v112
	v_lshlrev_b32_e32 v112, 1, v112
	v_mov_b32_e32 v113, v163
	v_lshl_add_u64 v[112:113], s[66:67], 0, v[112:113]
	v_lshl_add_u64 v[112:113], v[188:189], 1, v[112:113]
	global_store_dword v[112:113], v115, off
	s_nop 1
	v_mov_b32_dpp v115, v117 quad_perm:[1,0,3,2] row_mask:0xf bank_mask:0xf
	v_perm_b32 v116, v115, v117, v250
	v_add_co_u32_e32 v120, vcc, 0x22000, v112
	s_nop 1
	v_addc_co_u32_e32 v121, vcc, 0, v113, vcc
	global_store_dword v[120:121], v116, off offset:256
	s_nop 1
	v_mov_b32_dpp v116, v118 quad_perm:[1,0,3,2] row_mask:0xf bank_mask:0xf
	v_perm_b32 v115, v116, v118, v250
	s_waitcnt lgkmcnt(0)
	s_nop 1
	v_mov_b32_dpp v116, v119 quad_perm:[1,0,3,2] row_mask:0xf bank_mask:0xf
	v_add_co_u32_e32 v120, vcc, 0x44000, v112
	s_nop 1
	v_addc_co_u32_e32 v121, vcc, 0, v113, vcc
	global_store_dword v[120:121], v115, off offset:512
	v_perm_b32 v114, v116, v119, v250
	v_add_co_u32_e32 v112, vcc, 0x66000, v112
	s_nop 1
	v_addc_co_u32_e32 v113, vcc, 0, v113, vcc
	global_store_dword v[112:113], v114, off offset:768
.LBB0_571:
	v_or_b32_e32 v114, 16, v210
	v_mov_b64_e32 v[112:113], s[64:65]
	v_mad_i64_i32 v[112:113], s[16:17], v114, s47, v[112:113]
	v_mov_b32_e32 v114, v144
	v_mov_b32_e32 v115, v148
	s_waitcnt lgkmcnt(0)
	v_pk_mul_f32 v[116:117], v[108:109], v[114:115]
	v_mov_b32_e32 v120, v150
	v_sub_f32_e32 v116, v116, v117
	v_mul_f32_e32 v118, v215, v116
	v_mov_b32_e32 v116, v148
	v_mov_b32_e32 v117, v144
	v_pk_mul_f32 v[108:109], v[108:109], v[116:117]
	v_mov_b32_e32 v148, v145
	v_add_f32_e32 v108, v109, v108
	v_mul_f32_e32 v108, v215, v108
	v_mov_b32_e32 v144, v149
	v_cvt_pk_bf16_f32 v108, v118, v108
	v_pk_mul_f32 v[118:119], v[110:111], v[148:149]
	v_pk_mul_f32 v[110:111], v[110:111], v[144:145]
	v_sub_f32_e32 v109, v118, v119
	v_add_f32_e32 v110, v111, v110
	v_mul_f32_e32 v109, v215, v109
	v_mul_f32_e32 v110, v215, v110
	v_mov_b32_e32 v118, v146
	v_mov_b32_e32 v119, v150
	v_mov_b32_e32 v121, v146
	v_cvt_pk_bf16_f32 v109, v109, v110
	v_pk_mul_f32 v[110:111], v[104:105], v[118:119]
	v_pk_mul_f32 v[104:105], v[104:105], v[120:121]
	v_sub_f32_e32 v110, v110, v111
	v_add_f32_e32 v104, v105, v104
	v_mul_f32_e32 v110, v215, v110
	v_mul_f32_e32 v104, v215, v104
	v_mov_b32_e32 v150, v147
	v_cvt_pk_bf16_f32 v110, v110, v104
	v_pk_mul_f32 v[104:105], v[106:107], v[150:151]
	v_mov_b32_e32 v146, v151
	v_sub_f32_e32 v104, v104, v105
	v_mul_f32_e32 v111, v215, v104
	v_pk_mul_f32 v[104:105], v[106:107], v[146:147]
	v_ashrrev_i32_e32 v122, 31, v210
	v_lshl_add_u64 v[112:113], v[162:163], 1, v[112:113]
	v_add_f32_e32 v104, v105, v104
	s_and_b64 vcc, exec, s[6:7]
	v_mul_f32_e32 v104, v215, v104
	v_cvt_pk_bf16_f32 v111, v111, v104
	global_store_dwordx4 v[112:113], v[108:111], off
	s_cbranch_vccnz .LBB0_589
	v_cmp_lt_i32_e32 vcc, v228, v222
	s_nop 1
	v_cndmask_b32_e32 v104, v221, v228, vcc
	v_lshlrev_b32_e32 v106, 2, v104
	s_nop 1
	v_mov_b32_dpp v104, v108 quad_perm:[1,0,3,2] row_mask:0xf bank_mask:0xf
	v_perm_b32 v107, v104, v108, v250
	s_waitcnt lgkmcnt(0)
	v_or_b32_e32 v104, s71, v204
	v_mul_u32_u24_e32 v104, 0x8840, v104
	v_lshlrev_b32_e32 v104, 1, v104
	v_mov_b32_e32 v105, v163
	v_sub_co_u32_e32 v124, vcc, v210, v176
	v_lshl_add_u64 v[104:105], s[66:67], 0, v[104:105]
	s_nop 0
	v_subbrev_co_u32_e32 v125, vcc, 0, v122, vcc
	v_lshl_add_u64 v[104:105], v[124:125], 1, v[104:105]
	global_store_dword v[104:105], v107, off offset:32
	s_nop 1
	v_mov_b32_dpp v107, v109 quad_perm:[1,0,3,2] row_mask:0xf bank_mask:0xf
	v_perm_b32 v108, v107, v109, v250
	v_lshl_add_u64 v[104:105], v[104:105], 0, 32
	v_add_co_u32_e32 v124, vcc, 0x22000, v104
	s_nop 1
	v_addc_co_u32_e32 v125, vcc, 0, v105, vcc
	global_store_dword v[124:125], v108, off offset:256
	s_nop 1
	v_mov_b32_dpp v108, v110 quad_perm:[1,0,3,2] row_mask:0xf bank_mask:0xf
	v_perm_b32 v107, v108, v110, v250
	s_waitcnt lgkmcnt(0)
	s_nop 1
	v_mov_b32_dpp v108, v111 quad_perm:[1,0,3,2] row_mask:0xf bank_mask:0xf
	v_add_co_u32_e32 v124, vcc, 0x44000, v104
	s_nop 1
	v_addc_co_u32_e32 v125, vcc, 0, v105, vcc
	global_store_dword v[124:125], v107, off offset:512
	v_perm_b32 v106, v108, v111, v250
	v_add_co_u32_e32 v104, vcc, 0x66000, v104
	s_nop 1
	v_addc_co_u32_e32 v105, vcc, 0, v105, vcc
	global_store_dword v[104:105], v106, off offset:768
; __device__ __forceinline__ unsigned cvt_pk_bf16(float lo, float hi) { unsigned r; asm volatile("v_cvt_pk_bf16_f32 %0, %1, %2" : "=v"(r) : "v"(lo), "v"(hi)); return r; }
;     __device__ __forceinline__ void operator()(const f32x4 (&acc)[2][2][4][2], const Unit& u, int wr, int wc, int fr, int fq) const {
;     ...
;                 for (int m = 0; m < 4; ++m) { bf16_t* rowp = O + (size_t)(row0 + ai * HALF + m * 16) * 3072 + col0;
; #pragma unroll
;                     for (int bj = 0; bj < 2; ++bj) {
;                         const float s_ = sc[m][bj]; const f32x4 cc = c4[m], ss = s4[m];
;                         const f32x4 v0 = acc[ai][bj][m][0], v1 = acc[ai][bj][m][1];
;                         u32x4 w;
;                         w.x = cvt_pk_bf16((v0[0] * cc[0] - v0[1] * ss[0]) * s_, (v0[0] * ss[0] + v0[1] * cc[0]) * s_);
;                         w.y = cvt_pk_bf16((v0[2] * cc[1] - v0[3] * ss[1]) * s_, (v0[2] * ss[1] + v0[3] * cc[1]) * s_);
;                         w.z = cvt_pk_bf16((v1[0] * cc[2] - v1[1] * ss[2]) * s_, (v1[0] * ss[2] + v1[1] * cc[2]) * s_);
;                         w.w = cvt_pk_bf16((v1[2] * cc[3] - v1[3] * ss[3]) * s_, (v1[2] * ss[3] + v1[3] * cc[3]) * s_);
;                         *(u32x4*)(rowp + bj * HALF) = w;
;                         if (u.pn >= 8) {
;                             const int tokrow = row0 + ai * HALF + m * 16, odd = fr & 1;
;                             bf16_t* kt = KT + (size_t)((hb + bj) * 128 + wc * 32 + 8 * fq + odd) * ldk + (tokrow - odd);
; #pragma unroll
;                             for (int q = 0; q < 4; ++q) { const unsigned mine = w[q], other = (unsigned)__shfl_xor((int)mine, 1);
;                                 const unsigned pr = odd ? ((other >> 16) | (mine & 0xffff0000u)) : ((mine & 0xffffu) | (other << 16));
;                                 *(unsigned*)(kt + (size_t)(2 * q) * ldk) = pr; }
;                         }
.LBB0_589:
	v_pk_mul_f32 v[104:105], v[100:101], v[114:115]
	v_pk_mul_f32 v[100:101], v[100:101], v[116:117]
	v_sub_f32_e32 v104, v104, v105
	v_add_f32_e32 v100, v101, v100
	v_mul_f32_e32 v104, v214, v104
	v_mul_f32_e32 v100, v214, v100
	v_cvt_pk_bf16_f32 v100, v104, v100
	v_pk_mul_f32 v[104:105], v[102:103], v[148:149]
	v_pk_mul_f32 v[102:103], v[102:103], v[144:145]
	v_sub_f32_e32 v101, v104, v105
	v_add_f32_e32 v102, v103, v102
	v_mul_f32_e32 v101, v214, v101
	v_mul_f32_e32 v102, v214, v102
	v_cvt_pk_bf16_f32 v101, v101, v102
	v_pk_mul_f32 v[102:103], v[96:97], v[118:119]
	v_pk_mul_f32 v[96:97], v[96:97], v[120:121]
	v_sub_f32_e32 v102, v102, v103
	v_add_f32_e32 v96, v97, v96
	v_mul_f32_e32 v102, v214, v102
	v_mul_f32_e32 v96, v214, v96
	v_cvt_pk_bf16_f32 v102, v102, v96
	v_pk_mul_f32 v[96:97], v[98:99], v[150:151]
	s_and_b64 vcc, exec, s[6:7]
	v_sub_f32_e32 v96, v96, v97
	v_mul_f32_e32 v103, v214, v96
	v_pk_mul_f32 v[96:97], v[98:99], v[146:147]
	s_nop 0
	v_add_f32_e32 v96, v97, v96
	v_mul_f32_e32 v96, v214, v96
	v_cvt_pk_bf16_f32 v103, v103, v96
	global_store_dwordx4 v[112:113], v[100:103], off offset:256
	s_cbranch_vccnz .LBB0_607
	v_cmp_lt_i32_e32 vcc, v228, v222
	s_nop 1
	v_cndmask_b32_e32 v96, v221, v228, vcc
	v_lshlrev_b32_e32 v98, 2, v96
	s_nop 1
	v_mov_b32_dpp v96, v100 quad_perm:[1,0,3,2] row_mask:0xf bank_mask:0xf
	v_perm_b32 v99, v96, v100, v250
	s_waitcnt lgkmcnt(0)
	v_or_b32_e32 v96, s71, v207
	v_mul_u32_u24_e32 v96, 0x8840, v96
	v_lshlrev_b32_e32 v96, 1, v96
	v_mov_b32_e32 v97, v163
	v_sub_co_u32_e32 v104, vcc, v210, v176
	v_lshl_add_u64 v[96:97], s[66:67], 0, v[96:97]
	s_nop 0
	v_subbrev_co_u32_e32 v105, vcc, 0, v122, vcc
	v_lshl_add_u64 v[96:97], v[104:105], 1, v[96:97]
	global_store_dword v[96:97], v99, off offset:32
	s_nop 1
	v_mov_b32_dpp v99, v101 quad_perm:[1,0,3,2] row_mask:0xf bank_mask:0xf
	v_perm_b32 v100, v99, v101, v250
	v_lshl_add_u64 v[96:97], v[96:97], 0, 32
	v_add_co_u32_e32 v104, vcc, 0x22000, v96
	s_nop 1
	v_addc_co_u32_e32 v105, vcc, 0, v97, vcc
	global_store_dword v[104:105], v100, off offset:256
	s_nop 1
	v_mov_b32_dpp v100, v102 quad_perm:[1,0,3,2] row_mask:0xf bank_mask:0xf
	v_perm_b32 v99, v100, v102, v250
	s_waitcnt lgkmcnt(0)
	s_nop 1
	v_mov_b32_dpp v100, v103 quad_perm:[1,0,3,2] row_mask:0xf bank_mask:0xf
	v_add_co_u32_e32 v104, vcc, 0x44000, v96
	s_nop 1
	v_addc_co_u32_e32 v105, vcc, 0, v97, vcc
	global_store_dword v[104:105], v99, off offset:512
	v_perm_b32 v98, v100, v103, v250
	v_add_co_u32_e32 v96, vcc, 0x66000, v96
	s_nop 1
	v_addc_co_u32_e32 v97, vcc, 0, v97, vcc
	global_store_dword v[96:97], v98, off offset:768
.LBB0_607:
	v_or_b32_e32 v98, 32, v210
	v_mov_b64_e32 v[96:97], s[64:65]
	v_mad_i64_i32 v[96:97], s[16:17], v98, s47, v[96:97]
	v_mov_b32_e32 v98, v136
	v_mov_b32_e32 v99, v140
	s_waitcnt lgkmcnt(0)
	v_pk_mul_f32 v[100:101], v[92:93], v[98:99]
	v_mov_b32_e32 v104, v142
	v_sub_f32_e32 v100, v100, v101
	v_mul_f32_e32 v102, v213, v100
	v_mov_b32_e32 v100, v140
	v_mov_b32_e32 v101, v136
	v_pk_mul_f32 v[92:93], v[92:93], v[100:101]
	v_mov_b32_e32 v140, v137
	v_add_f32_e32 v92, v93, v92
	v_mul_f32_e32 v92, v213, v92
	v_mov_b32_e32 v136, v141
	v_cvt_pk_bf16_f32 v92, v102, v92
	v_pk_mul_f32 v[102:103], v[94:95], v[140:141]
	v_pk_mul_f32 v[94:95], v[94:95], v[136:137]
	v_sub_f32_e32 v93, v102, v103
	v_add_f32_e32 v94, v95, v94
	v_mul_f32_e32 v93, v213, v93
	v_mul_f32_e32 v94, v213, v94
	v_mov_b32_e32 v102, v138
	v_mov_b32_e32 v103, v142
	v_mov_b32_e32 v105, v138
	v_cvt_pk_bf16_f32 v93, v93, v94
	v_pk_mul_f32 v[94:95], v[88:89], v[102:103]
	v_pk_mul_f32 v[88:89], v[88:89], v[104:105]
	v_sub_f32_e32 v94, v94, v95
	v_add_f32_e32 v88, v89, v88
	v_mul_f32_e32 v94, v213, v94
	v_mul_f32_e32 v88, v213, v88
	v_mov_b32_e32 v142, v139
	v_cvt_pk_bf16_f32 v94, v94, v88
	v_pk_mul_f32 v[88:89], v[90:91], v[142:143]
	v_mov_b32_e32 v138, v143
	v_sub_f32_e32 v88, v88, v89
	v_mul_f32_e32 v95, v213, v88
	v_pk_mul_f32 v[88:89], v[90:91], v[138:139]
	v_lshl_add_u64 v[96:97], v[162:163], 1, v[96:97]
	v_add_f32_e32 v88, v89, v88
	s_and_b64 vcc, exec, s[6:7]
	v_mul_f32_e32 v88, v213, v88
	v_cvt_pk_bf16_f32 v95, v95, v88
	global_store_dwordx4 v[96:97], v[92:95], off
	s_cbranch_vccnz .LBB0_625
	v_cmp_lt_i32_e32 vcc, v228, v222
	s_nop 1
	v_cndmask_b32_e32 v88, v221, v228, vcc
	v_lshlrev_b32_e32 v90, 2, v88
	s_nop 1
	v_mov_b32_dpp v88, v92 quad_perm:[1,0,3,2] row_mask:0xf bank_mask:0xf
	v_perm_b32 v91, v88, v92, v250
	s_waitcnt lgkmcnt(0)
	v_or_b32_e32 v88, s71, v204
	v_mul_u32_u24_e32 v88, 0x8840, v88
	v_lshlrev_b32_e32 v88, 1, v88
	v_mov_b32_e32 v89, v163
	v_sub_co_u32_e32 v106, vcc, v210, v176
	v_lshl_add_u64 v[88:89], s[66:67], 0, v[88:89]
	s_nop 0
	v_subbrev_co_u32_e32 v107, vcc, 0, v122, vcc
	v_lshl_add_u64 v[88:89], v[106:107], 1, v[88:89]
	global_store_dword v[88:89], v91, off offset:64
	s_nop 1
	v_mov_b32_dpp v91, v93 quad_perm:[1,0,3,2] row_mask:0xf bank_mask:0xf
	v_perm_b32 v92, v91, v93, v250
	v_lshl_add_u64 v[88:89], v[88:89], 0, 64
	v_add_co_u32_e32 v106, vcc, 0x22000, v88
	s_nop 1
	v_addc_co_u32_e32 v107, vcc, 0, v89, vcc
	global_store_dword v[106:107], v92, off offset:256
	s_nop 1
	v_mov_b32_dpp v92, v94 quad_perm:[1,0,3,2] row_mask:0xf bank_mask:0xf
	v_perm_b32 v91, v92, v94, v250
	s_waitcnt lgkmcnt(0)
	s_nop 1
	v_mov_b32_dpp v92, v95 quad_perm:[1,0,3,2] row_mask:0xf bank_mask:0xf
	v_add_co_u32_e32 v106, vcc, 0x44000, v88
	s_nop 1
	v_addc_co_u32_e32 v107, vcc, 0, v89, vcc
	global_store_dword v[106:107], v91, off offset:512
	v_perm_b32 v90, v92, v95, v250
	v_add_co_u32_e32 v88, vcc, 0x66000, v88
	s_nop 1
	v_addc_co_u32_e32 v89, vcc, 0, v89, vcc
	global_store_dword v[88:89], v90, off offset:768
; __device__ __forceinline__ unsigned cvt_pk_bf16(float lo, float hi) { unsigned r; asm volatile("v_cvt_pk_bf16_f32 %0, %1, %2" : "=v"(r) : "v"(lo), "v"(hi)); return r; }
;     __device__ __forceinline__ void operator()(const f32x4 (&acc)[2][2][4][2], const Unit& u, int wr, int wc, int fr, int fq) const {
;     ...
;                 for (int m = 0; m < 4; ++m) { bf16_t* rowp = O + (size_t)(row0 + ai * HALF + m * 16) * 3072 + col0;
; #pragma unroll
;                     for (int bj = 0; bj < 2; ++bj) {
;                         const float s_ = sc[m][bj]; const f32x4 cc = c4[m], ss = s4[m];
;                         const f32x4 v0 = acc[ai][bj][m][0], v1 = acc[ai][bj][m][1];
;                         u32x4 w;
;                         w.x = cvt_pk_bf16((v0[0] * cc[0] - v0[1] * ss[0]) * s_, (v0[0] * ss[0] + v0[1] * cc[0]) * s_);
;                         w.y = cvt_pk_bf16((v0[2] * cc[1] - v0[3] * ss[1]) * s_, (v0[2] * ss[1] + v0[3] * cc[1]) * s_);
;                         w.z = cvt_pk_bf16((v1[0] * cc[2] - v1[1] * ss[2]) * s_, (v1[0] * ss[2] + v1[1] * cc[2]) * s_);
;                         w.w = cvt_pk_bf16((v1[2] * cc[3] - v1[3] * ss[3]) * s_, (v1[2] * ss[3] + v1[3] * cc[3]) * s_);
;                         *(u32x4*)(rowp + bj * HALF) = w;
;                         if (u.pn >= 8) {
;                             const int tokrow = row0 + ai * HALF + m * 16, odd = fr & 1;
;                             bf16_t* kt = KT + (size_t)((hb + bj) * 128 + wc * 32 + 8 * fq + odd) * ldk + (tokrow - odd);
; #pragma unroll
;                             for (int q = 0; q < 4; ++q) { const unsigned mine = w[q], other = (unsigned)__shfl_xor((int)mine, 1);
;                                 const unsigned pr = odd ? ((other >> 16) | (mine & 0xffff0000u)) : ((mine & 0xffffu) | (other << 16));
;                                 *(unsigned*)(kt + (size_t)(2 * q) * ldk) = pr; }
;                         }
.LBB0_625:
	v_pk_mul_f32 v[88:89], v[84:85], v[98:99]
	v_pk_mul_f32 v[84:85], v[84:85], v[100:101]
	v_sub_f32_e32 v88, v88, v89
	v_add_f32_e32 v84, v85, v84
	v_mul_f32_e32 v88, v212, v88
	v_mul_f32_e32 v84, v212, v84
	v_cvt_pk_bf16_f32 v84, v88, v84
	v_pk_mul_f32 v[88:89], v[86:87], v[140:141]
	v_pk_mul_f32 v[86:87], v[86:87], v[136:137]
	v_sub_f32_e32 v85, v88, v89
	v_add_f32_e32 v86, v87, v86
	v_mul_f32_e32 v85, v212, v85
	v_mul_f32_e32 v86, v212, v86
	v_cvt_pk_bf16_f32 v85, v85, v86
	v_pk_mul_f32 v[86:87], v[80:81], v[102:103]
	v_pk_mul_f32 v[80:81], v[80:81], v[104:105]
	v_sub_f32_e32 v86, v86, v87
	v_add_f32_e32 v80, v81, v80
	v_mul_f32_e32 v86, v212, v86
	v_mul_f32_e32 v80, v212, v80
	v_cvt_pk_bf16_f32 v86, v86, v80
	v_pk_mul_f32 v[80:81], v[82:83], v[142:143]
	s_and_b64 vcc, exec, s[6:7]
	v_sub_f32_e32 v80, v80, v81
	v_mul_f32_e32 v87, v212, v80
	v_pk_mul_f32 v[80:81], v[82:83], v[138:139]
	s_nop 0
	v_add_f32_e32 v80, v81, v80
	v_mul_f32_e32 v80, v212, v80
	v_cvt_pk_bf16_f32 v87, v87, v80
	global_store_dwordx4 v[96:97], v[84:87], off offset:256
	s_cbranch_vccnz .LBB0_643
	v_cmp_lt_i32_e32 vcc, v228, v222
	s_nop 1
	v_cndmask_b32_e32 v80, v221, v228, vcc
	v_lshlrev_b32_e32 v82, 2, v80
	s_nop 1
	v_mov_b32_dpp v80, v84 quad_perm:[1,0,3,2] row_mask:0xf bank_mask:0xf
	v_perm_b32 v83, v80, v84, v250
	s_waitcnt lgkmcnt(0)
	v_or_b32_e32 v80, s71, v207
	v_mul_u32_u24_e32 v80, 0x8840, v80
	v_lshlrev_b32_e32 v80, 1, v80
	v_mov_b32_e32 v81, v163
	v_sub_co_u32_e32 v88, vcc, v210, v176
	v_lshl_add_u64 v[80:81], s[66:67], 0, v[80:81]
	s_nop 0
	v_subbrev_co_u32_e32 v89, vcc, 0, v122, vcc
	v_lshl_add_u64 v[80:81], v[88:89], 1, v[80:81]
	global_store_dword v[80:81], v83, off offset:64
	s_nop 1
	v_mov_b32_dpp v83, v85 quad_perm:[1,0,3,2] row_mask:0xf bank_mask:0xf
	v_perm_b32 v84, v83, v85, v250
	v_lshl_add_u64 v[80:81], v[80:81], 0, 64
	v_add_co_u32_e32 v88, vcc, 0x22000, v80
	s_nop 1
	v_addc_co_u32_e32 v89, vcc, 0, v81, vcc
	global_store_dword v[88:89], v84, off offset:256
	s_nop 1
	v_mov_b32_dpp v84, v86 quad_perm:[1,0,3,2] row_mask:0xf bank_mask:0xf
	v_perm_b32 v83, v84, v86, v250
	s_waitcnt lgkmcnt(0)
	s_nop 1
	v_mov_b32_dpp v84, v87 quad_perm:[1,0,3,2] row_mask:0xf bank_mask:0xf
	v_add_co_u32_e32 v88, vcc, 0x44000, v80
	s_nop 1
	v_addc_co_u32_e32 v89, vcc, 0, v81, vcc
	global_store_dword v[88:89], v83, off offset:512
	v_perm_b32 v82, v84, v87, v250
	v_add_co_u32_e32 v80, vcc, 0x66000, v80
	s_nop 1
	v_addc_co_u32_e32 v81, vcc, 0, v81, vcc
	global_store_dword v[80:81], v82, off offset:768
.LBB0_643:
	v_or_b32_e32 v82, 48, v210
	v_mov_b64_e32 v[80:81], s[64:65]
	v_mad_i64_i32 v[80:81], s[16:17], v82, s47, v[80:81]
	v_mov_b32_e32 v82, v128
	v_mov_b32_e32 v83, v132
	s_waitcnt lgkmcnt(0)
	v_pk_mul_f32 v[84:85], v[76:77], v[82:83]
	v_mov_b32_e32 v88, v134
	v_sub_f32_e32 v84, v84, v85
	v_mul_f32_e32 v86, v211, v84
	v_mov_b32_e32 v84, v132
	v_mov_b32_e32 v85, v128
	v_pk_mul_f32 v[76:77], v[76:77], v[84:85]
	v_mov_b32_e32 v132, v129
	v_add_f32_e32 v76, v77, v76
	v_mul_f32_e32 v76, v211, v76
	v_mov_b32_e32 v128, v133
	v_cvt_pk_bf16_f32 v76, v86, v76
	v_pk_mul_f32 v[86:87], v[78:79], v[132:133]
	v_pk_mul_f32 v[78:79], v[78:79], v[128:129]
	v_sub_f32_e32 v77, v86, v87
	v_add_f32_e32 v78, v79, v78
	v_mul_f32_e32 v77, v211, v77
	v_mul_f32_e32 v78, v211, v78
	v_mov_b32_e32 v86, v130
	v_mov_b32_e32 v87, v134
	v_mov_b32_e32 v89, v130
	v_cvt_pk_bf16_f32 v77, v77, v78
	v_pk_mul_f32 v[78:79], v[72:73], v[86:87]
	v_pk_mul_f32 v[72:73], v[72:73], v[88:89]
	v_sub_f32_e32 v78, v78, v79
	v_add_f32_e32 v72, v73, v72
	v_mul_f32_e32 v78, v211, v78
	v_mul_f32_e32 v72, v211, v72
	v_mov_b32_e32 v134, v131
	v_cvt_pk_bf16_f32 v78, v78, v72
	v_pk_mul_f32 v[72:73], v[74:75], v[134:135]
	v_mov_b32_e32 v130, v135
	v_sub_f32_e32 v72, v72, v73
	v_mul_f32_e32 v79, v211, v72
	v_pk_mul_f32 v[72:73], v[74:75], v[130:131]
	v_lshl_add_u64 v[80:81], v[162:163], 1, v[80:81]
	v_add_f32_e32 v72, v73, v72
	s_and_b64 vcc, exec, s[6:7]
	v_mul_f32_e32 v72, v211, v72
	v_cvt_pk_bf16_f32 v79, v79, v72
	global_store_dwordx4 v[80:81], v[76:79], off
	s_cbranch_vccnz .LBB0_661
	v_cmp_lt_i32_e32 vcc, v228, v222
	s_nop 1
	v_cndmask_b32_e32 v72, v221, v228, vcc
	v_lshlrev_b32_e32 v74, 2, v72
	s_nop 1
	v_mov_b32_dpp v72, v76 quad_perm:[1,0,3,2] row_mask:0xf bank_mask:0xf
	v_perm_b32 v75, v72, v76, v250
	s_waitcnt lgkmcnt(0)
	v_or_b32_e32 v72, s71, v204
	v_mul_u32_u24_e32 v72, 0x8840, v72
	v_lshlrev_b32_e32 v72, 1, v72
	v_mov_b32_e32 v73, v163
	v_sub_co_u32_e32 v90, vcc, v210, v176
	v_lshl_add_u64 v[72:73], s[66:67], 0, v[72:73]
	s_nop 0
	v_subbrev_co_u32_e32 v91, vcc, 0, v122, vcc
	v_lshl_add_u64 v[72:73], v[90:91], 1, v[72:73]
	global_store_dword v[72:73], v75, off offset:96
	s_nop 1
	v_mov_b32_dpp v75, v77 quad_perm:[1,0,3,2] row_mask:0xf bank_mask:0xf
	v_perm_b32 v76, v75, v77, v250
	v_lshl_add_u64 v[72:73], v[72:73], 0, s[36:37]
	v_add_co_u32_e32 v90, vcc, 0x22000, v72
	s_nop 1
	v_addc_co_u32_e32 v91, vcc, 0, v73, vcc
	global_store_dword v[90:91], v76, off offset:256
	s_nop 1
	v_mov_b32_dpp v76, v78 quad_perm:[1,0,3,2] row_mask:0xf bank_mask:0xf
	v_perm_b32 v75, v76, v78, v250
	s_waitcnt lgkmcnt(0)
	s_nop 1
	v_mov_b32_dpp v76, v79 quad_perm:[1,0,3,2] row_mask:0xf bank_mask:0xf
	v_add_co_u32_e32 v90, vcc, 0x44000, v72
	s_nop 1
	v_addc_co_u32_e32 v91, vcc, 0, v73, vcc
	global_store_dword v[90:91], v75, off offset:512
	v_perm_b32 v74, v76, v79, v250
	v_add_co_u32_e32 v72, vcc, 0x66000, v72
	s_nop 1
	v_addc_co_u32_e32 v73, vcc, 0, v73, vcc
	global_store_dword v[72:73], v74, off offset:768
; __device__ __forceinline__ unsigned cvt_pk_bf16(float lo, float hi) { unsigned r; asm volatile("v_cvt_pk_bf16_f32 %0, %1, %2" : "=v"(r) : "v"(lo), "v"(hi)); return r; }
;     __device__ __forceinline__ void operator()(const f32x4 (&acc)[2][2][4][2], const Unit& u, int wr, int wc, int fr, int fq) const {
;     ...
;                 for (int m = 0; m < 4; ++m) { const int row = row0 + ai * HALF + m * 16, t = row & 4095, p = t & 127;
;                     c4[m] = *(const f32x4*)(cs + t * 64 + 16 * wc + 4 * fq); s4[m] = *(const f32x4*)(sn + t * 64 + 16 * wc + 4 * fq);
;                     sc[m][0] = dtab[hb * 128 + p]; sc[m][1] = dtab[(hb + 1) * 128 + p]; }
;                 __builtin_amdgcn_sched_barrier(0);
; #pragma unroll
;                 for (int m = 0; m < 4; ++m) { bf16_t* rowp = O + (size_t)(row0 + ai * HALF + m * 16) * 3072 + col0;
; #pragma unroll
;                     for (int bj = 0; bj < 2; ++bj) {
;                         const float s_ = sc[m][bj]; const f32x4 cc = c4[m], ss = s4[m];
;                         const f32x4 v0 = acc[ai][bj][m][0], v1 = acc[ai][bj][m][1];
;                         u32x4 w;
;                         w.x = cvt_pk_bf16((v0[0] * cc[0] - v0[1] * ss[0]) * s_, (v0[0] * ss[0] + v0[1] * cc[0]) * s_);
;                         w.y = cvt_pk_bf16((v0[2] * cc[1] - v0[3] * ss[1]) * s_, (v0[2] * ss[1] + v0[3] * cc[1]) * s_);
;                         w.z = cvt_pk_bf16((v1[0] * cc[2] - v1[1] * ss[2]) * s_, (v1[0] * ss[2] + v1[1] * cc[2]) * s_);
;                         w.w = cvt_pk_bf16((v1[2] * cc[3] - v1[3] * ss[3]) * s_, (v1[2] * ss[3] + v1[3] * cc[3]) * s_);
;                         *(u32x4*)(rowp + bj * HALF) = w;
;                         if (u.pn >= 8) {
;                             const int tokrow = row0 + ai * HALF + m * 16, odd = fr & 1;
;                             bf16_t* kt = KT + (size_t)((hb + bj) * 128 + wc * 32 + 8 * fq + odd) * ldk + (tokrow - odd);
; #pragma unroll
;                             for (int q = 0; q < 4; ++q) { const unsigned mine = w[q], other = (unsigned)__shfl_xor((int)mine, 1);
;                                 const unsigned pr = odd ? ((other >> 16) | (mine & 0xffff0000u)) : ((mine & 0xffffu) | (other << 16));
;                                 *(unsigned*)(kt + (size_t)(2 * q) * ldk) = pr; }
;                         }
.LBB0_661:
	v_pk_mul_f32 v[72:73], v[68:69], v[82:83]
	v_pk_mul_f32 v[68:69], v[68:69], v[84:85]
	v_sub_f32_e32 v72, v72, v73
	v_add_f32_e32 v68, v69, v68
	v_mul_f32_e32 v72, v187, v72
	v_mul_f32_e32 v68, v187, v68
	v_cvt_pk_bf16_f32 v68, v72, v68
	v_pk_mul_f32 v[72:73], v[70:71], v[132:133]
	v_pk_mul_f32 v[70:71], v[70:71], v[128:129]
	v_sub_f32_e32 v69, v72, v73
	v_add_f32_e32 v70, v71, v70
	v_mul_f32_e32 v69, v187, v69
	v_mul_f32_e32 v70, v187, v70
	v_cvt_pk_bf16_f32 v69, v69, v70
	v_pk_mul_f32 v[70:71], v[64:65], v[86:87]
	v_pk_mul_f32 v[64:65], v[64:65], v[88:89]
	v_sub_f32_e32 v70, v70, v71
	v_add_f32_e32 v64, v65, v64
	v_mul_f32_e32 v70, v187, v70
	v_mul_f32_e32 v64, v187, v64
	v_cvt_pk_bf16_f32 v70, v70, v64
	v_pk_mul_f32 v[64:65], v[66:67], v[134:135]
	s_and_b64 vcc, exec, s[6:7]
	v_sub_f32_e32 v64, v64, v65
	v_mul_f32_e32 v71, v187, v64
	v_pk_mul_f32 v[64:65], v[66:67], v[130:131]
	s_nop 0
	v_add_f32_e32 v64, v65, v64
	v_mul_f32_e32 v64, v187, v64
	v_cvt_pk_bf16_f32 v71, v71, v64
	global_store_dwordx4 v[80:81], v[68:71], off offset:256
	s_cbranch_vccnz .LBB0_679
	v_cmp_lt_i32_e32 vcc, v228, v222
	s_nop 1
	v_cndmask_b32_e32 v64, v221, v228, vcc
	v_lshlrev_b32_e32 v66, 2, v64
	s_nop 1
	v_mov_b32_dpp v64, v68 quad_perm:[1,0,3,2] row_mask:0xf bank_mask:0xf
	v_perm_b32 v67, v64, v68, v250
	s_waitcnt lgkmcnt(0)
	v_or_b32_e32 v64, s71, v207
	v_mul_u32_u24_e32 v64, 0x8840, v64
	v_lshlrev_b32_e32 v64, 1, v64
	v_mov_b32_e32 v65, v163
	v_sub_co_u32_e32 v72, vcc, v210, v176
	v_lshl_add_u64 v[64:65], s[66:67], 0, v[64:65]
	s_nop 0
	v_subbrev_co_u32_e32 v73, vcc, 0, v122, vcc
	v_lshl_add_u64 v[64:65], v[72:73], 1, v[64:65]
	global_store_dword v[64:65], v67, off offset:96
	s_nop 1
	v_mov_b32_dpp v67, v69 quad_perm:[1,0,3,2] row_mask:0xf bank_mask:0xf
	v_perm_b32 v68, v67, v69, v250
	v_lshl_add_u64 v[64:65], v[64:65], 0, s[36:37]
	v_add_co_u32_e32 v72, vcc, 0x22000, v64
	s_nop 1
	v_addc_co_u32_e32 v73, vcc, 0, v65, vcc
	global_store_dword v[72:73], v68, off offset:256
	s_nop 1
	v_mov_b32_dpp v68, v70 quad_perm:[1,0,3,2] row_mask:0xf bank_mask:0xf
	v_perm_b32 v67, v68, v70, v250
	s_waitcnt lgkmcnt(0)
	s_nop 1
	v_mov_b32_dpp v68, v71 quad_perm:[1,0,3,2] row_mask:0xf bank_mask:0xf
	v_add_co_u32_e32 v72, vcc, 0x44000, v64
	s_nop 1
	v_addc_co_u32_e32 v73, vcc, 0, v65, vcc
	global_store_dword v[72:73], v67, off offset:512
	v_perm_b32 v66, v68, v71, v250
	v_add_co_u32_e32 v64, vcc, 0x66000, v64
	s_nop 1
	v_addc_co_u32_e32 v65, vcc, 0, v65, vcc
	global_store_dword v[64:65], v66, off offset:768
.LBB0_679:
	v_mov_b32_e32 v187, v163
	v_lshl_add_u64 v[64:65], s[78:79], 0, v[186:187]
	v_add_u32_e32 v98, 0x80, v210
	v_and_b32_e32 v70, 0xfcf, v98
	v_lshlrev_b32_e32 v66, 8, v70
	v_mov_b32_e32 v67, v163
	s_waitcnt lgkmcnt(0)
	v_lshl_add_u64 v[68:69], v[178:179], 0, v[66:67]
	v_lshl_add_u64 v[66:67], v[180:181], 0, v[66:67]
	global_load_dwordx4 v[88:91], v[68:69], off
	global_load_dwordx4 v[92:95], v[66:67], off
	global_load_dword v113, v[64:65], off
	global_load_dword v112, v[64:65], off offset:512
	v_or_b32_e32 v64, 16, v70
	s_movk_i32 s16, 0x5f
	v_lshlrev_b32_e32 v64, 8, v64
	v_mov_b32_e32 v65, v163
	v_bitop3_b32 v68, v70, s16, 16 bitop3:0xc8
	v_lshl_add_u64 v[66:67], v[178:179], 0, v[64:65]
	v_lshl_add_u64 v[64:65], v[180:181], 0, v[64:65]
	global_load_dwordx4 v[80:83], v[66:67], off
	global_load_dwordx4 v[84:87], v[64:65], off
	v_or_b32_e32 v64, s71, v68
	v_lshlrev_b32_e32 v64, 2, v64
	global_load_dword v111, v64, s[78:79]
	global_load_dword v110, v64, s[78:79] offset:512
	v_or_b32_e32 v64, 32, v70
	s_movk_i32 s16, 0x6f
	v_lshlrev_b32_e32 v64, 8, v64
	v_mov_b32_e32 v65, v163
	v_bitop3_b32 v68, v70, s16, 32 bitop3:0xc8
	v_lshl_add_u64 v[66:67], v[178:179], 0, v[64:65]
	v_lshl_add_u64 v[64:65], v[180:181], 0, v[64:65]
	global_load_dwordx4 v[72:75], v[66:67], off
	global_load_dwordx4 v[76:79], v[64:65], off
	v_or_b32_e32 v64, s71, v68
	v_lshlrev_b32_e32 v64, 2, v64
	s_movk_i32 s16, 0x7f
	global_load_dword v109, v64, s[78:79]
	global_load_dword v108, v64, s[78:79] offset:512
	v_or_b32_e32 v64, 48, v70
	v_bitop3_b32 v96, v70, s16, 48 bitop3:0xc8
	v_lshlrev_b32_e32 v64, 8, v64
	v_mov_b32_e32 v65, v163
	v_or_b32_e32 v96, s71, v96
	v_lshl_add_u64 v[66:67], v[178:179], 0, v[64:65]
	v_lshl_add_u64 v[68:69], v[180:181], 0, v[64:65]
	v_lshlrev_b32_e32 v96, 2, v96
	global_load_dwordx4 v[64:67], v[66:67], off
	s_nop 0
	global_load_dwordx4 v[68:71], v[68:69], off
	s_nop 0
	global_load_dword v107, v96, s[78:79]
	global_load_dword v106, v96, s[78:79] offset:512
	v_mov_b64_e32 v[96:97], s[64:65]
	v_mad_i64_i32 v[96:97], s[16:17], v98, s47, v[96:97]
	s_waitcnt vmcnt(15)
	v_mov_b32_e32 v98, v88
	s_waitcnt vmcnt(14)
	v_mov_b32_e32 v99, v92
	v_pk_mul_f32 v[100:101], v[60:61], v[98:99]
	v_mov_b32_e32 v104, v94
	v_sub_f32_e32 v100, v100, v101
	s_waitcnt vmcnt(13)
	v_mul_f32_e32 v102, v113, v100
	v_mov_b32_e32 v100, v92
	v_mov_b32_e32 v101, v88
	v_pk_mul_f32 v[60:61], v[60:61], v[100:101]
	v_mov_b32_e32 v92, v89
	v_add_f32_e32 v60, v61, v60
	v_mul_f32_e32 v60, v113, v60
	v_mov_b32_e32 v88, v93
	v_cvt_pk_bf16_f32 v60, v102, v60
	v_pk_mul_f32 v[102:103], v[62:63], v[92:93]
	v_pk_mul_f32 v[62:63], v[62:63], v[88:89]
	v_sub_f32_e32 v61, v102, v103
	v_add_f32_e32 v62, v63, v62
	v_mul_f32_e32 v61, v113, v61
	v_mul_f32_e32 v62, v113, v62
	v_mov_b32_e32 v102, v90
	v_mov_b32_e32 v103, v94
	v_mov_b32_e32 v105, v90
	v_cvt_pk_bf16_f32 v61, v61, v62
	v_pk_mul_f32 v[62:63], v[56:57], v[102:103]
	v_pk_mul_f32 v[56:57], v[56:57], v[104:105]
	v_sub_f32_e32 v62, v62, v63
	v_add_f32_e32 v56, v57, v56
	v_mul_f32_e32 v62, v113, v62
	v_mul_f32_e32 v56, v113, v56
	v_mov_b32_e32 v94, v91
	v_cvt_pk_bf16_f32 v62, v62, v56
	v_pk_mul_f32 v[56:57], v[58:59], v[94:95]
	v_mov_b32_e32 v90, v95
	v_sub_f32_e32 v56, v56, v57
	v_mul_f32_e32 v63, v113, v56
	v_pk_mul_f32 v[56:57], v[58:59], v[90:91]
	v_lshl_add_u64 v[96:97], v[162:163], 1, v[96:97]
	v_add_f32_e32 v56, v57, v56
	s_and_b64 vcc, exec, s[6:7]
	v_mul_f32_e32 v56, v113, v56
	v_cvt_pk_bf16_f32 v63, v63, v56
	global_store_dwordx4 v[96:97], v[60:63], off
	s_cbranch_vccnz .LBB0_697
; __device__ __forceinline__ unsigned cvt_pk_bf16(float lo, float hi) { unsigned r; asm volatile("v_cvt_pk_bf16_f32 %0, %1, %2" : "=v"(r) : "v"(lo), "v"(hi)); return r; }
;     __device__ __forceinline__ void operator()(const f32x4 (&acc)[2][2][4][2], const Unit& u, int wr, int wc, int fr, int fq) const {
;     ...
;                 for (int m = 0; m < 4; ++m) { bf16_t* rowp = O + (size_t)(row0 + ai * HALF + m * 16) * 3072 + col0;
; #pragma unroll
;                     for (int bj = 0; bj < 2; ++bj) {
;                         const float s_ = sc[m][bj]; const f32x4 cc = c4[m], ss = s4[m];
;                         const f32x4 v0 = acc[ai][bj][m][0], v1 = acc[ai][bj][m][1];
;                         u32x4 w;
;                         w.x = cvt_pk_bf16((v0[0] * cc[0] - v0[1] * ss[0]) * s_, (v0[0] * ss[0] + v0[1] * cc[0]) * s_);
;                         w.y = cvt_pk_bf16((v0[2] * cc[1] - v0[3] * ss[1]) * s_, (v0[2] * ss[1] + v0[3] * cc[1]) * s_);
;                         w.z = cvt_pk_bf16((v1[0] * cc[2] - v1[1] * ss[2]) * s_, (v1[0] * ss[2] + v1[1] * cc[2]) * s_);
;                         w.w = cvt_pk_bf16((v1[2] * cc[3] - v1[3] * ss[3]) * s_, (v1[2] * ss[3] + v1[3] * cc[3]) * s_);
;                         *(u32x4*)(rowp + bj * HALF) = w;
;                         if (u.pn >= 8) {
;                             const int tokrow = row0 + ai * HALF + m * 16, odd = fr & 1;
;                             bf16_t* kt = KT + (size_t)((hb + bj) * 128 + wc * 32 + 8 * fq + odd) * ldk + (tokrow - odd);
; #pragma unroll
;                             for (int q = 0; q < 4; ++q) { const unsigned mine = w[q], other = (unsigned)__shfl_xor((int)mine, 1);
;                                 const unsigned pr = odd ? ((other >> 16) | (mine & 0xffff0000u)) : ((mine & 0xffffu) | (other << 16));
;                                 *(unsigned*)(kt + (size_t)(2 * q) * ldk) = pr; }
;                         }
;                     } }
	v_cmp_lt_i32_e32 vcc, v228, v222
	s_nop 1
	v_cndmask_b32_e32 v56, v221, v228, vcc
	v_lshlrev_b32_e32 v58, 2, v56
	s_nop 1
	v_mov_b32_dpp v56, v60 quad_perm:[1,0,3,2] row_mask:0xf bank_mask:0xf
	v_perm_b32 v59, v56, v60, v250
	s_waitcnt lgkmcnt(0)
	v_or_b32_e32 v56, s71, v204
	v_mul_u32_u24_e32 v56, 0x8840, v56
	v_lshlrev_b32_e32 v56, 1, v56
	v_mov_b32_e32 v57, v163
	v_sub_co_u32_e32 v114, vcc, v210, v176
	v_lshl_add_u64 v[56:57], s[66:67], 0, v[56:57]
	s_nop 0
	v_subbrev_co_u32_e32 v115, vcc, 0, v122, vcc
	v_lshl_add_u64 v[56:57], v[114:115], 1, v[56:57]
	global_store_dword v[56:57], v59, off offset:256
	s_nop 1
	v_mov_b32_dpp v59, v61 quad_perm:[1,0,3,2] row_mask:0xf bank_mask:0xf
	v_perm_b32 v60, v59, v61, v250
	s_mov_b64 s[16:17], 0x100
	v_lshl_add_u64 v[56:57], v[56:57], 0, s[16:17]
	v_add_co_u32_e32 v114, vcc, 0x22000, v56
	s_nop 1
	v_addc_co_u32_e32 v115, vcc, 0, v57, vcc
	global_store_dword v[114:115], v60, off offset:256
	s_nop 1
	v_mov_b32_dpp v60, v62 quad_perm:[1,0,3,2] row_mask:0xf bank_mask:0xf
	v_perm_b32 v59, v60, v62, v250
	s_waitcnt lgkmcnt(0)
	s_nop 1
	v_mov_b32_dpp v60, v63 quad_perm:[1,0,3,2] row_mask:0xf bank_mask:0xf
	v_add_co_u32_e32 v114, vcc, 0x44000, v56
	s_nop 1
	v_addc_co_u32_e32 v115, vcc, 0, v57, vcc
	global_store_dword v[114:115], v59, off offset:512
	v_perm_b32 v58, v60, v63, v250
	v_add_co_u32_e32 v56, vcc, 0x66000, v56
	s_nop 1
	v_addc_co_u32_e32 v57, vcc, 0, v57, vcc
	global_store_dword v[56:57], v58, off offset:768
.LBB0_697:
	v_pk_mul_f32 v[56:57], v[52:53], v[98:99]
	v_pk_mul_f32 v[52:53], v[52:53], v[100:101]
	v_sub_f32_e32 v56, v56, v57
	v_add_f32_e32 v52, v53, v52
	s_waitcnt vmcnt(13)
	v_mul_f32_e32 v56, v112, v56
	v_mul_f32_e32 v52, v112, v52
	v_cvt_pk_bf16_f32 v52, v56, v52
	v_pk_mul_f32 v[56:57], v[54:55], v[92:93]
	v_pk_mul_f32 v[54:55], v[54:55], v[88:89]
	v_sub_f32_e32 v53, v56, v57
	v_add_f32_e32 v54, v55, v54
	v_mul_f32_e32 v53, v112, v53
	v_mul_f32_e32 v54, v112, v54
	v_cvt_pk_bf16_f32 v53, v53, v54
	v_pk_mul_f32 v[54:55], v[48:49], v[102:103]
	v_pk_mul_f32 v[48:49], v[48:49], v[104:105]
	v_sub_f32_e32 v54, v54, v55
	v_add_f32_e32 v48, v49, v48
	v_mul_f32_e32 v54, v112, v54
	v_mul_f32_e32 v48, v112, v48
	v_cvt_pk_bf16_f32 v54, v54, v48
	v_pk_mul_f32 v[48:49], v[50:51], v[94:95]
	s_and_b64 vcc, exec, s[6:7]
	v_sub_f32_e32 v48, v48, v49
	v_mul_f32_e32 v55, v112, v48
	v_pk_mul_f32 v[48:49], v[50:51], v[90:91]
	s_nop 0
	v_add_f32_e32 v48, v49, v48
	v_mul_f32_e32 v48, v112, v48
	v_cvt_pk_bf16_f32 v55, v55, v48
	global_store_dwordx4 v[96:97], v[52:55], off offset:256
	s_cbranch_vccnz .LBB0_715
	v_cmp_lt_i32_e32 vcc, v228, v222
	s_nop 1
	v_cndmask_b32_e32 v48, v221, v228, vcc
	v_lshlrev_b32_e32 v50, 2, v48
	s_nop 1
	v_mov_b32_dpp v48, v52 quad_perm:[1,0,3,2] row_mask:0xf bank_mask:0xf
	v_perm_b32 v51, v48, v52, v250
	s_waitcnt lgkmcnt(0)
	v_or_b32_e32 v48, s71, v207
	v_mul_u32_u24_e32 v48, 0x8840, v48
	v_lshlrev_b32_e32 v48, 1, v48
	v_mov_b32_e32 v49, v163
	v_sub_co_u32_e32 v56, vcc, v210, v176
	v_lshl_add_u64 v[48:49], s[66:67], 0, v[48:49]
	s_nop 0
	v_subbrev_co_u32_e32 v57, vcc, 0, v122, vcc
	v_lshl_add_u64 v[48:49], v[56:57], 1, v[48:49]
	global_store_dword v[48:49], v51, off offset:256
	s_nop 1
	v_mov_b32_dpp v51, v53 quad_perm:[1,0,3,2] row_mask:0xf bank_mask:0xf
	v_perm_b32 v52, v51, v53, v250
	s_mov_b64 s[16:17], 0x100
	v_lshl_add_u64 v[48:49], v[48:49], 0, s[16:17]
	v_add_co_u32_e32 v56, vcc, 0x22000, v48
	s_nop 1
	v_addc_co_u32_e32 v57, vcc, 0, v49, vcc
	global_store_dword v[56:57], v52, off offset:256
	s_nop 1
	v_mov_b32_dpp v52, v54 quad_perm:[1,0,3,2] row_mask:0xf bank_mask:0xf
	v_perm_b32 v51, v52, v54, v250
	s_waitcnt lgkmcnt(0)
	s_nop 1
	v_mov_b32_dpp v52, v55 quad_perm:[1,0,3,2] row_mask:0xf bank_mask:0xf
	v_add_co_u32_e32 v56, vcc, 0x44000, v48
	s_nop 1
	v_addc_co_u32_e32 v57, vcc, 0, v49, vcc
	global_store_dword v[56:57], v51, off offset:512
	v_perm_b32 v50, v52, v55, v250
	v_add_co_u32_e32 v48, vcc, 0x66000, v48
	s_nop 1
	v_addc_co_u32_e32 v49, vcc, 0, v49, vcc
	global_store_dword v[48:49], v50, off offset:768
.LBB0_715:
	v_add_u32_e32 v50, 0x90, v210
	v_mov_b64_e32 v[48:49], s[64:65]
	v_mad_i64_i32 v[48:49], s[16:17], v50, s47, v[48:49]
	s_waitcnt vmcnt(13)
	v_mov_b32_e32 v50, v80
	s_waitcnt vmcnt(12)
	v_mov_b32_e32 v51, v84
	s_waitcnt lgkmcnt(0)
	v_pk_mul_f32 v[52:53], v[44:45], v[50:51]
	v_mov_b32_e32 v56, v86
	v_sub_f32_e32 v52, v52, v53
	s_waitcnt vmcnt(11)
	v_mul_f32_e32 v54, v111, v52
	v_mov_b32_e32 v52, v84
	v_mov_b32_e32 v53, v80
	v_pk_mul_f32 v[44:45], v[44:45], v[52:53]
	v_mov_b32_e32 v84, v81
	v_add_f32_e32 v44, v45, v44
	v_mul_f32_e32 v44, v111, v44
	v_mov_b32_e32 v80, v85
	v_cvt_pk_bf16_f32 v44, v54, v44
	v_pk_mul_f32 v[54:55], v[46:47], v[84:85]
	v_pk_mul_f32 v[46:47], v[46:47], v[80:81]
	v_sub_f32_e32 v45, v54, v55
	v_add_f32_e32 v46, v47, v46
	v_mul_f32_e32 v45, v111, v45
	v_mul_f32_e32 v46, v111, v46
	v_mov_b32_e32 v54, v82
	v_mov_b32_e32 v55, v86
	v_mov_b32_e32 v57, v82
	v_cvt_pk_bf16_f32 v45, v45, v46
	v_pk_mul_f32 v[46:47], v[40:41], v[54:55]
	v_pk_mul_f32 v[40:41], v[40:41], v[56:57]
	v_sub_f32_e32 v46, v46, v47
	v_add_f32_e32 v40, v41, v40
	v_mul_f32_e32 v46, v111, v46
	v_mul_f32_e32 v40, v111, v40
	v_mov_b32_e32 v86, v83
	v_cvt_pk_bf16_f32 v46, v46, v40
	v_pk_mul_f32 v[40:41], v[42:43], v[86:87]
	v_mov_b32_e32 v82, v87
	v_sub_f32_e32 v40, v40, v41
	v_mul_f32_e32 v47, v111, v40
	v_pk_mul_f32 v[40:41], v[42:43], v[82:83]
	v_lshl_add_u64 v[48:49], v[162:163], 1, v[48:49]
	v_add_f32_e32 v40, v41, v40
	s_and_b64 vcc, exec, s[6:7]
	v_mul_f32_e32 v40, v111, v40
	v_cvt_pk_bf16_f32 v47, v47, v40
	global_store_dwordx4 v[48:49], v[44:47], off
	s_cbranch_vccnz .LBB0_733
; __device__ __forceinline__ unsigned cvt_pk_bf16(float lo, float hi) { unsigned r; asm volatile("v_cvt_pk_bf16_f32 %0, %1, %2" : "=v"(r) : "v"(lo), "v"(hi)); return r; }
;     __device__ __forceinline__ void operator()(const f32x4 (&acc)[2][2][4][2], const Unit& u, int wr, int wc, int fr, int fq) const {
;     ...
;                 for (int m = 0; m < 4; ++m) { bf16_t* rowp = O + (size_t)(row0 + ai * HALF + m * 16) * 3072 + col0;
; #pragma unroll
;                     for (int bj = 0; bj < 2; ++bj) {
;                         const float s_ = sc[m][bj]; const f32x4 cc = c4[m], ss = s4[m];
;                         const f32x4 v0 = acc[ai][bj][m][0], v1 = acc[ai][bj][m][1];
;                         u32x4 w;
;                         w.x = cvt_pk_bf16((v0[0] * cc[0] - v0[1] * ss[0]) * s_, (v0[0] * ss[0] + v0[1] * cc[0]) * s_);
;                         w.y = cvt_pk_bf16((v0[2] * cc[1] - v0[3] * ss[1]) * s_, (v0[2] * ss[1] + v0[3] * cc[1]) * s_);
;                         w.z = cvt_pk_bf16((v1[0] * cc[2] - v1[1] * ss[2]) * s_, (v1[0] * ss[2] + v1[1] * cc[2]) * s_);
;                         w.w = cvt_pk_bf16((v1[2] * cc[3] - v1[3] * ss[3]) * s_, (v1[2] * ss[3] + v1[3] * cc[3]) * s_);
;                         *(u32x4*)(rowp + bj * HALF) = w;
;                         if (u.pn >= 8) {
;                             const int tokrow = row0 + ai * HALF + m * 16, odd = fr & 1;
;                             bf16_t* kt = KT + (size_t)((hb + bj) * 128 + wc * 32 + 8 * fq + odd) * ldk + (tokrow - odd);
; #pragma unroll
;                             for (int q = 0; q < 4; ++q) { const unsigned mine = w[q], other = (unsigned)__shfl_xor((int)mine, 1);
;                                 const unsigned pr = odd ? ((other >> 16) | (mine & 0xffff0000u)) : ((mine & 0xffffu) | (other << 16));
;                                 *(unsigned*)(kt + (size_t)(2 * q) * ldk) = pr; }
;                         }
;                     } }
	v_cmp_lt_i32_e32 vcc, v228, v222
	s_nop 1
	v_cndmask_b32_e32 v40, v221, v228, vcc
	v_lshlrev_b32_e32 v42, 2, v40
	s_nop 1
	v_mov_b32_dpp v40, v44 quad_perm:[1,0,3,2] row_mask:0xf bank_mask:0xf
	v_perm_b32 v43, v40, v44, v250
	s_waitcnt lgkmcnt(0)
	v_or_b32_e32 v40, s71, v204
	v_mul_u32_u24_e32 v40, 0x8840, v40
	v_lshlrev_b32_e32 v40, 1, v40
	v_mov_b32_e32 v41, v163
	v_sub_co_u32_e32 v58, vcc, v210, v176
	v_lshl_add_u64 v[40:41], s[66:67], 0, v[40:41]
	s_nop 0
	v_subbrev_co_u32_e32 v59, vcc, 0, v122, vcc
	v_lshl_add_u64 v[40:41], v[58:59], 1, v[40:41]
	global_store_dword v[40:41], v43, off offset:288
	s_nop 1
	v_mov_b32_dpp v43, v45 quad_perm:[1,0,3,2] row_mask:0xf bank_mask:0xf
	v_perm_b32 v44, v43, v45, v250
	v_lshl_add_u64 v[40:41], v[40:41], 0, s[38:39]
	v_add_co_u32_e32 v58, vcc, 0x22000, v40
	s_nop 1
	v_addc_co_u32_e32 v59, vcc, 0, v41, vcc
	global_store_dword v[58:59], v44, off offset:256
	s_nop 1
	v_mov_b32_dpp v44, v46 quad_perm:[1,0,3,2] row_mask:0xf bank_mask:0xf
	v_perm_b32 v43, v44, v46, v250
	s_waitcnt lgkmcnt(0)
	s_nop 1
	v_mov_b32_dpp v44, v47 quad_perm:[1,0,3,2] row_mask:0xf bank_mask:0xf
	v_add_co_u32_e32 v58, vcc, 0x44000, v40
	s_nop 1
	v_addc_co_u32_e32 v59, vcc, 0, v41, vcc
	global_store_dword v[58:59], v43, off offset:512
	v_perm_b32 v42, v44, v47, v250
	v_add_co_u32_e32 v40, vcc, 0x66000, v40
	s_nop 1
	v_addc_co_u32_e32 v41, vcc, 0, v41, vcc
	global_store_dword v[40:41], v42, off offset:768
.LBB0_733:
	v_pk_mul_f32 v[40:41], v[36:37], v[50:51]
	v_pk_mul_f32 v[36:37], v[36:37], v[52:53]
	v_sub_f32_e32 v40, v40, v41
	v_add_f32_e32 v36, v37, v36
	s_waitcnt vmcnt(11)
	v_mul_f32_e32 v40, v110, v40
	v_mul_f32_e32 v36, v110, v36
	v_cvt_pk_bf16_f32 v36, v40, v36
	v_pk_mul_f32 v[40:41], v[38:39], v[84:85]
	v_pk_mul_f32 v[38:39], v[38:39], v[80:81]
	v_sub_f32_e32 v37, v40, v41
	v_add_f32_e32 v38, v39, v38
	v_mul_f32_e32 v37, v110, v37
	v_mul_f32_e32 v38, v110, v38
	v_cvt_pk_bf16_f32 v37, v37, v38
	v_pk_mul_f32 v[38:39], v[32:33], v[54:55]
	v_pk_mul_f32 v[32:33], v[32:33], v[56:57]
	v_sub_f32_e32 v38, v38, v39
	v_add_f32_e32 v32, v33, v32
	v_mul_f32_e32 v38, v110, v38
	v_mul_f32_e32 v32, v110, v32
	v_cvt_pk_bf16_f32 v38, v38, v32
	v_pk_mul_f32 v[32:33], v[34:35], v[86:87]
	s_and_b64 vcc, exec, s[6:7]
	v_sub_f32_e32 v32, v32, v33
	v_mul_f32_e32 v39, v110, v32
	v_pk_mul_f32 v[32:33], v[34:35], v[82:83]
	s_nop 0
	v_add_f32_e32 v32, v33, v32
	v_mul_f32_e32 v32, v110, v32
	v_cvt_pk_bf16_f32 v39, v39, v32
	global_store_dwordx4 v[48:49], v[36:39], off offset:256
	s_cbranch_vccnz .LBB0_751
	v_cmp_lt_i32_e32 vcc, v228, v222
	s_nop 1
	v_cndmask_b32_e32 v32, v221, v228, vcc
	v_lshlrev_b32_e32 v34, 2, v32
	s_nop 1
	v_mov_b32_dpp v32, v36 quad_perm:[1,0,3,2] row_mask:0xf bank_mask:0xf
	v_perm_b32 v35, v32, v36, v250
	s_waitcnt lgkmcnt(0)
	v_or_b32_e32 v32, s71, v207
	v_mul_u32_u24_e32 v32, 0x8840, v32
	v_lshlrev_b32_e32 v32, 1, v32
	v_mov_b32_e32 v33, v163
	v_sub_co_u32_e32 v40, vcc, v210, v176
	v_lshl_add_u64 v[32:33], s[66:67], 0, v[32:33]
	s_nop 0
	v_subbrev_co_u32_e32 v41, vcc, 0, v122, vcc
	v_lshl_add_u64 v[32:33], v[40:41], 1, v[32:33]
	global_store_dword v[32:33], v35, off offset:288
	s_nop 1
	v_mov_b32_dpp v35, v37 quad_perm:[1,0,3,2] row_mask:0xf bank_mask:0xf
	v_perm_b32 v36, v35, v37, v250
	v_lshl_add_u64 v[32:33], v[32:33], 0, s[38:39]
	v_add_co_u32_e32 v40, vcc, 0x22000, v32
	s_nop 1
	v_addc_co_u32_e32 v41, vcc, 0, v33, vcc
	global_store_dword v[40:41], v36, off offset:256
	s_nop 1
	v_mov_b32_dpp v36, v38 quad_perm:[1,0,3,2] row_mask:0xf bank_mask:0xf
	v_perm_b32 v35, v36, v38, v250
	s_waitcnt lgkmcnt(0)
	s_nop 1
	v_mov_b32_dpp v36, v39 quad_perm:[1,0,3,2] row_mask:0xf bank_mask:0xf
	v_add_co_u32_e32 v40, vcc, 0x44000, v32
	s_nop 1
	v_addc_co_u32_e32 v41, vcc, 0, v33, vcc
	global_store_dword v[40:41], v35, off offset:512
	v_perm_b32 v34, v36, v39, v250
	v_add_co_u32_e32 v32, vcc, 0x66000, v32
	s_nop 1
	v_addc_co_u32_e32 v33, vcc, 0, v33, vcc
	global_store_dword v[32:33], v34, off offset:768
.LBB0_751:
	v_add_u32_e32 v34, 0xa0, v210
	v_mov_b64_e32 v[32:33], s[64:65]
	v_mad_i64_i32 v[32:33], s[16:17], v34, s47, v[32:33]
	s_waitcnt vmcnt(11)
	v_mov_b32_e32 v34, v72
	s_waitcnt vmcnt(10)
	v_mov_b32_e32 v35, v76
	s_waitcnt lgkmcnt(0)
	v_pk_mul_f32 v[36:37], v[28:29], v[34:35]
	v_mov_b32_e32 v40, v78
	v_sub_f32_e32 v36, v36, v37
	s_waitcnt vmcnt(9)
	v_mul_f32_e32 v38, v109, v36
	v_mov_b32_e32 v36, v76
	v_mov_b32_e32 v37, v72
	v_pk_mul_f32 v[28:29], v[28:29], v[36:37]
	v_mov_b32_e32 v76, v73
	v_add_f32_e32 v28, v29, v28
	v_mul_f32_e32 v28, v109, v28
	v_mov_b32_e32 v72, v77
	v_cvt_pk_bf16_f32 v28, v38, v28
	v_pk_mul_f32 v[38:39], v[30:31], v[76:77]
	v_pk_mul_f32 v[30:31], v[30:31], v[72:73]
	v_sub_f32_e32 v29, v38, v39
	v_add_f32_e32 v30, v31, v30
	v_mul_f32_e32 v29, v109, v29
	v_mul_f32_e32 v30, v109, v30
	v_mov_b32_e32 v38, v74
	v_mov_b32_e32 v39, v78
	v_mov_b32_e32 v41, v74
	v_cvt_pk_bf16_f32 v29, v29, v30
	v_pk_mul_f32 v[30:31], v[24:25], v[38:39]
	v_pk_mul_f32 v[24:25], v[24:25], v[40:41]
	v_sub_f32_e32 v30, v30, v31
	v_add_f32_e32 v24, v25, v24
	v_mul_f32_e32 v30, v109, v30
	v_mul_f32_e32 v24, v109, v24
	v_mov_b32_e32 v78, v75
	v_cvt_pk_bf16_f32 v30, v30, v24
	v_pk_mul_f32 v[24:25], v[26:27], v[78:79]
	v_mov_b32_e32 v74, v79
	v_sub_f32_e32 v24, v24, v25
	v_mul_f32_e32 v31, v109, v24
	v_pk_mul_f32 v[24:25], v[26:27], v[74:75]
	v_lshl_add_u64 v[32:33], v[162:163], 1, v[32:33]
	v_add_f32_e32 v24, v25, v24
	s_and_b64 vcc, exec, s[6:7]
	v_mul_f32_e32 v24, v109, v24
	v_cvt_pk_bf16_f32 v31, v31, v24
	global_store_dwordx4 v[32:33], v[28:31], off
	s_cbranch_vccnz .LBB0_769
	v_cmp_lt_i32_e32 vcc, v228, v222
	s_nop 1
	v_cndmask_b32_e32 v24, v221, v228, vcc
	v_lshlrev_b32_e32 v26, 2, v24
	s_nop 1
	v_mov_b32_dpp v24, v28 quad_perm:[1,0,3,2] row_mask:0xf bank_mask:0xf
	v_perm_b32 v27, v24, v28, v250
	s_waitcnt lgkmcnt(0)
	v_or_b32_e32 v24, s71, v204
	v_mul_u32_u24_e32 v24, 0x8840, v24
	v_lshlrev_b32_e32 v24, 1, v24
	v_mov_b32_e32 v25, v163
	v_sub_co_u32_e32 v42, vcc, v210, v176
	v_lshl_add_u64 v[24:25], s[66:67], 0, v[24:25]
	s_nop 0
	v_subbrev_co_u32_e32 v43, vcc, 0, v122, vcc
	v_lshl_add_u64 v[24:25], v[42:43], 1, v[24:25]
	global_store_dword v[24:25], v27, off offset:320
	s_nop 1
	v_mov_b32_dpp v27, v29 quad_perm:[1,0,3,2] row_mask:0xf bank_mask:0xf
	v_perm_b32 v28, v27, v29, v250
	v_lshl_add_u64 v[24:25], v[24:25], 0, s[40:41]
	v_add_co_u32_e32 v42, vcc, 0x22000, v24
	s_nop 1
	v_addc_co_u32_e32 v43, vcc, 0, v25, vcc
	global_store_dword v[42:43], v28, off offset:256
	s_nop 1
	v_mov_b32_dpp v28, v30 quad_perm:[1,0,3,2] row_mask:0xf bank_mask:0xf
	v_perm_b32 v27, v28, v30, v250
	s_waitcnt lgkmcnt(0)
	s_nop 1
	v_mov_b32_dpp v28, v31 quad_perm:[1,0,3,2] row_mask:0xf bank_mask:0xf
	v_add_co_u32_e32 v42, vcc, 0x44000, v24
	s_nop 1
	v_addc_co_u32_e32 v43, vcc, 0, v25, vcc
	global_store_dword v[42:43], v27, off offset:512
	v_perm_b32 v26, v28, v31, v250
	v_add_co_u32_e32 v24, vcc, 0x66000, v24
	s_nop 1
	v_addc_co_u32_e32 v25, vcc, 0, v25, vcc
	global_store_dword v[24:25], v26, off offset:768
; __device__ __forceinline__ unsigned cvt_pk_bf16(float lo, float hi) { unsigned r; asm volatile("v_cvt_pk_bf16_f32 %0, %1, %2" : "=v"(r) : "v"(lo), "v"(hi)); return r; }
;     __device__ __forceinline__ void operator()(const f32x4 (&acc)[2][2][4][2], const Unit& u, int wr, int wc, int fr, int fq) const {
;     ...
;                 for (int m = 0; m < 4; ++m) { bf16_t* rowp = O + (size_t)(row0 + ai * HALF + m * 16) * 3072 + col0;
; #pragma unroll
;                     for (int bj = 0; bj < 2; ++bj) {
;                         const float s_ = sc[m][bj]; const f32x4 cc = c4[m], ss = s4[m];
;                         const f32x4 v0 = acc[ai][bj][m][0], v1 = acc[ai][bj][m][1];
;                         u32x4 w;
;                         w.x = cvt_pk_bf16((v0[0] * cc[0] - v0[1] * ss[0]) * s_, (v0[0] * ss[0] + v0[1] * cc[0]) * s_);
;                         w.y = cvt_pk_bf16((v0[2] * cc[1] - v0[3] * ss[1]) * s_, (v0[2] * ss[1] + v0[3] * cc[1]) * s_);
;                         w.z = cvt_pk_bf16((v1[0] * cc[2] - v1[1] * ss[2]) * s_, (v1[0] * ss[2] + v1[1] * cc[2]) * s_);
;                         w.w = cvt_pk_bf16((v1[2] * cc[3] - v1[3] * ss[3]) * s_, (v1[2] * ss[3] + v1[3] * cc[3]) * s_);
;                         *(u32x4*)(rowp + bj * HALF) = w;
;                         if (u.pn >= 8) {
;                             const int tokrow = row0 + ai * HALF + m * 16, odd = fr & 1;
;                             bf16_t* kt = KT + (size_t)((hb + bj) * 128 + wc * 32 + 8 * fq + odd) * ldk + (tokrow - odd);
; #pragma unroll
;                             for (int q = 0; q < 4; ++q) { const unsigned mine = w[q], other = (unsigned)__shfl_xor((int)mine, 1);
;                                 const unsigned pr = odd ? ((other >> 16) | (mine & 0xffff0000u)) : ((mine & 0xffffu) | (other << 16));
;                                 *(unsigned*)(kt + (size_t)(2 * q) * ldk) = pr; }
;                         }
;                     } }
.LBB0_769:
	v_pk_mul_f32 v[24:25], v[20:21], v[34:35]
	v_pk_mul_f32 v[20:21], v[20:21], v[36:37]
	v_sub_f32_e32 v24, v24, v25
	v_add_f32_e32 v20, v21, v20
	s_waitcnt vmcnt(9)
	v_mul_f32_e32 v24, v108, v24
	v_mul_f32_e32 v20, v108, v20
	v_cvt_pk_bf16_f32 v20, v24, v20
	v_pk_mul_f32 v[24:25], v[22:23], v[76:77]
	v_pk_mul_f32 v[22:23], v[22:23], v[72:73]
	v_sub_f32_e32 v21, v24, v25
	v_add_f32_e32 v22, v23, v22
	v_mul_f32_e32 v21, v108, v21
	v_mul_f32_e32 v22, v108, v22
	v_cvt_pk_bf16_f32 v21, v21, v22
	v_pk_mul_f32 v[22:23], v[16:17], v[38:39]
	v_pk_mul_f32 v[16:17], v[16:17], v[40:41]
	v_sub_f32_e32 v22, v22, v23
	v_add_f32_e32 v16, v17, v16
	v_mul_f32_e32 v22, v108, v22
	v_mul_f32_e32 v16, v108, v16
	v_cvt_pk_bf16_f32 v22, v22, v16
	v_pk_mul_f32 v[16:17], v[18:19], v[78:79]
	s_and_b64 vcc, exec, s[6:7]
	v_sub_f32_e32 v16, v16, v17
	v_mul_f32_e32 v23, v108, v16
	v_pk_mul_f32 v[16:17], v[18:19], v[74:75]
	s_nop 0
	v_add_f32_e32 v16, v17, v16
	v_mul_f32_e32 v16, v108, v16
	v_cvt_pk_bf16_f32 v23, v23, v16
	global_store_dwordx4 v[32:33], v[20:23], off offset:256
	s_cbranch_vccnz .LBB0_787
	v_cmp_lt_i32_e32 vcc, v228, v222
	s_nop 1
	v_cndmask_b32_e32 v16, v221, v228, vcc
	v_lshlrev_b32_e32 v18, 2, v16
	s_nop 1
	v_mov_b32_dpp v16, v20 quad_perm:[1,0,3,2] row_mask:0xf bank_mask:0xf
	v_perm_b32 v19, v16, v20, v250
	s_waitcnt lgkmcnt(0)
	v_or_b32_e32 v16, s71, v207
	v_mul_u32_u24_e32 v16, 0x8840, v16
	v_lshlrev_b32_e32 v16, 1, v16
	v_mov_b32_e32 v17, v163
	v_sub_co_u32_e32 v24, vcc, v210, v176
	v_lshl_add_u64 v[16:17], s[66:67], 0, v[16:17]
	s_nop 0
	v_subbrev_co_u32_e32 v25, vcc, 0, v122, vcc
	v_lshl_add_u64 v[16:17], v[24:25], 1, v[16:17]
	global_store_dword v[16:17], v19, off offset:320
	s_nop 1
	v_mov_b32_dpp v19, v21 quad_perm:[1,0,3,2] row_mask:0xf bank_mask:0xf
	v_perm_b32 v20, v19, v21, v250
	v_lshl_add_u64 v[16:17], v[16:17], 0, s[40:41]
	v_add_co_u32_e32 v24, vcc, 0x22000, v16
	s_nop 1
	v_addc_co_u32_e32 v25, vcc, 0, v17, vcc
	global_store_dword v[24:25], v20, off offset:256
	s_nop 1
	v_mov_b32_dpp v20, v22 quad_perm:[1,0,3,2] row_mask:0xf bank_mask:0xf
	v_perm_b32 v19, v20, v22, v250
	s_waitcnt lgkmcnt(0)
	s_nop 1
	v_mov_b32_dpp v20, v23 quad_perm:[1,0,3,2] row_mask:0xf bank_mask:0xf
	v_add_co_u32_e32 v24, vcc, 0x44000, v16
	s_nop 1
	v_addc_co_u32_e32 v25, vcc, 0, v17, vcc
	global_store_dword v[24:25], v19, off offset:512
	v_perm_b32 v18, v20, v23, v250
	v_add_co_u32_e32 v16, vcc, 0x66000, v16
	s_nop 1
	v_addc_co_u32_e32 v17, vcc, 0, v17, vcc
	global_store_dword v[16:17], v18, off offset:768
; __device__ __forceinline__ unsigned cvt_pk_bf16(float lo, float hi) { unsigned r; asm volatile("v_cvt_pk_bf16_f32 %0, %1, %2" : "=v"(r) : "v"(lo), "v"(hi)); return r; }
;     __device__ __forceinline__ void operator()(const f32x4 (&acc)[2][2][4][2], const Unit& u, int wr, int wc, int fr, int fq) const {
;     ...
;                 for (int m = 0; m < 4; ++m) { bf16_t* rowp = O + (size_t)(row0 + ai * HALF + m * 16) * 3072 + col0;
; #pragma unroll
;                     for (int bj = 0; bj < 2; ++bj) {
;                         const float s_ = sc[m][bj]; const f32x4 cc = c4[m], ss = s4[m];
;                         const f32x4 v0 = acc[ai][bj][m][0], v1 = acc[ai][bj][m][1];
;                         u32x4 w;
;                         w.x = cvt_pk_bf16((v0[0] * cc[0] - v0[1] * ss[0]) * s_, (v0[0] * ss[0] + v0[1] * cc[0]) * s_);
;                         w.y = cvt_pk_bf16((v0[2] * cc[1] - v0[3] * ss[1]) * s_, (v0[2] * ss[1] + v0[3] * cc[1]) * s_);
;                         w.z = cvt_pk_bf16((v1[0] * cc[2] - v1[1] * ss[2]) * s_, (v1[0] * ss[2] + v1[1] * cc[2]) * s_);
;                         w.w = cvt_pk_bf16((v1[2] * cc[3] - v1[3] * ss[3]) * s_, (v1[2] * ss[3] + v1[3] * cc[3]) * s_);
;                         *(u32x4*)(rowp + bj * HALF) = w;
;                         if (u.pn >= 8) {
;                             const int tokrow = row0 + ai * HALF + m * 16, odd = fr & 1;
;                             bf16_t* kt = KT + (size_t)((hb + bj) * 128 + wc * 32 + 8 * fq + odd) * ldk + (tokrow - odd);
; #pragma unroll
;                             for (int q = 0; q < 4; ++q) { const unsigned mine = w[q], other = (unsigned)__shfl_xor((int)mine, 1);
;                                 const unsigned pr = odd ? ((other >> 16) | (mine & 0xffff0000u)) : ((mine & 0xffffu) | (other << 16));
;                                 *(unsigned*)(kt + (size_t)(2 * q) * ldk) = pr; }
;                         }
;                     } }
.LBB0_787:
	v_add_u32_e32 v18, 0xb0, v210
	v_mov_b64_e32 v[16:17], s[64:65]
	v_mad_i64_i32 v[16:17], s[16:17], v18, s47, v[16:17]
	s_waitcnt vmcnt(9)
	v_mov_b32_e32 v18, v64
	s_waitcnt vmcnt(8)
	v_mov_b32_e32 v19, v68
	s_waitcnt lgkmcnt(0)
	v_pk_mul_f32 v[20:21], v[12:13], v[18:19]
	v_mov_b32_e32 v24, v70
	v_sub_f32_e32 v20, v20, v21
	s_waitcnt vmcnt(7)
	v_mul_f32_e32 v22, v107, v20
	v_mov_b32_e32 v20, v68
	v_mov_b32_e32 v21, v64
	v_pk_mul_f32 v[12:13], v[12:13], v[20:21]
	v_mov_b32_e32 v68, v65
	v_add_f32_e32 v12, v13, v12
	v_mul_f32_e32 v12, v107, v12
	v_mov_b32_e32 v64, v69
	v_cvt_pk_bf16_f32 v12, v22, v12
	v_pk_mul_f32 v[22:23], v[14:15], v[68:69]
	v_pk_mul_f32 v[14:15], v[14:15], v[64:65]
	v_sub_f32_e32 v13, v22, v23
	v_add_f32_e32 v14, v15, v14
	v_mul_f32_e32 v13, v107, v13
	v_mul_f32_e32 v14, v107, v14
	v_mov_b32_e32 v22, v66
	v_mov_b32_e32 v23, v70
	v_mov_b32_e32 v25, v66
	v_cvt_pk_bf16_f32 v13, v13, v14
	v_pk_mul_f32 v[14:15], v[8:9], v[22:23]
	v_pk_mul_f32 v[8:9], v[8:9], v[24:25]
	v_sub_f32_e32 v14, v14, v15
	v_add_f32_e32 v8, v9, v8
	v_mul_f32_e32 v14, v107, v14
	v_mul_f32_e32 v8, v107, v8
	v_mov_b32_e32 v70, v67
	v_cvt_pk_bf16_f32 v14, v14, v8
	v_pk_mul_f32 v[8:9], v[10:11], v[70:71]
	v_mov_b32_e32 v66, v71
	v_sub_f32_e32 v8, v8, v9
	v_mul_f32_e32 v15, v107, v8
	v_pk_mul_f32 v[8:9], v[10:11], v[66:67]
	v_lshl_add_u64 v[16:17], v[162:163], 1, v[16:17]
	v_add_f32_e32 v8, v9, v8
	s_and_b64 vcc, exec, s[6:7]
	v_mul_f32_e32 v8, v107, v8
	v_cvt_pk_bf16_f32 v15, v15, v8
	global_store_dwordx4 v[16:17], v[12:15], off
	s_cbranch_vccnz .LBB0_805
	v_cmp_lt_i32_e32 vcc, v228, v222
	s_nop 1
	v_cndmask_b32_e32 v8, v221, v228, vcc
	v_lshlrev_b32_e32 v10, 2, v8
	s_nop 1
	v_mov_b32_dpp v8, v12 quad_perm:[1,0,3,2] row_mask:0xf bank_mask:0xf
	v_perm_b32 v11, v8, v12, v250
	s_waitcnt lgkmcnt(0)
	v_or_b32_e32 v8, s71, v204
	v_mul_u32_u24_e32 v8, 0x8840, v8
	v_lshlrev_b32_e32 v162, 1, v8
	v_sub_co_u32_e32 v26, vcc, v210, v176
	v_lshl_add_u64 v[8:9], s[66:67], 0, v[162:163]
	s_nop 0
	v_subbrev_co_u32_e32 v27, vcc, 0, v122, vcc
	v_lshl_add_u64 v[8:9], v[26:27], 1, v[8:9]
	global_store_dword v[8:9], v11, off offset:352
	s_nop 1
	v_mov_b32_dpp v11, v13 quad_perm:[1,0,3,2] row_mask:0xf bank_mask:0xf
	v_perm_b32 v12, v11, v13, v250
	v_lshl_add_u64 v[8:9], v[8:9], 0, s[42:43]
	v_add_co_u32_e32 v26, vcc, 0x22000, v8
	s_nop 1
	v_addc_co_u32_e32 v27, vcc, 0, v9, vcc
	global_store_dword v[26:27], v12, off offset:256
	s_nop 1
	v_mov_b32_dpp v12, v14 quad_perm:[1,0,3,2] row_mask:0xf bank_mask:0xf
	v_perm_b32 v11, v12, v14, v250
	s_waitcnt lgkmcnt(0)
	s_nop 1
	v_mov_b32_dpp v12, v15 quad_perm:[1,0,3,2] row_mask:0xf bank_mask:0xf
	v_add_co_u32_e32 v26, vcc, 0x44000, v8
	s_nop 1
	v_addc_co_u32_e32 v27, vcc, 0, v9, vcc
	global_store_dword v[26:27], v11, off offset:512
	v_perm_b32 v10, v12, v15, v250
	v_add_co_u32_e32 v8, vcc, 0x66000, v8
	s_nop 1
	v_addc_co_u32_e32 v9, vcc, 0, v9, vcc
	global_store_dword v[8:9], v10, off offset:768
.LBB0_805:
	v_pk_mul_f32 v[8:9], v[4:5], v[18:19]
	v_pk_mul_f32 v[4:5], v[4:5], v[20:21]
	v_sub_f32_e32 v8, v8, v9
	v_add_f32_e32 v4, v5, v4
	s_waitcnt vmcnt(7)
	v_mul_f32_e32 v8, v106, v8
	v_mul_f32_e32 v4, v106, v4
	v_cvt_pk_bf16_f32 v4, v8, v4
	v_pk_mul_f32 v[8:9], v[6:7], v[68:69]
	v_pk_mul_f32 v[6:7], v[6:7], v[64:65]
	v_sub_f32_e32 v5, v8, v9
	v_add_f32_e32 v6, v7, v6
	v_mul_f32_e32 v5, v106, v5
	v_mul_f32_e32 v6, v106, v6
	v_cvt_pk_bf16_f32 v5, v5, v6
	v_pk_mul_f32 v[6:7], v[0:1], v[22:23]
	v_pk_mul_f32 v[0:1], v[0:1], v[24:25]
	v_sub_f32_e32 v6, v6, v7
	v_add_f32_e32 v0, v1, v0
	v_mul_f32_e32 v6, v106, v6
	v_mul_f32_e32 v0, v106, v0
	v_cvt_pk_bf16_f32 v6, v6, v0
	v_pk_mul_f32 v[0:1], v[2:3], v[70:71]
	s_and_b64 vcc, exec, s[6:7]
	v_sub_f32_e32 v0, v0, v1
	v_mul_f32_e32 v7, v106, v0
	v_pk_mul_f32 v[0:1], v[2:3], v[66:67]
	s_nop 0
	v_add_f32_e32 v0, v1, v0
	v_mul_f32_e32 v0, v106, v0
	v_cvt_pk_bf16_f32 v7, v7, v0
	global_store_dwordx4 v[16:17], v[4:7], off offset:256
	s_cbranch_vccnz .LBB0_823
	v_cmp_lt_i32_e32 vcc, v228, v222
	s_nop 1
	v_cndmask_b32_e32 v0, v221, v228, vcc
	v_lshlrev_b32_e32 v2, 2, v0
	s_nop 1
	v_mov_b32_dpp v0, v4 quad_perm:[1,0,3,2] row_mask:0xf bank_mask:0xf
	v_perm_b32 v3, v0, v4, v250
	s_waitcnt lgkmcnt(0)
	v_or_b32_e32 v0, s71, v207
	v_mul_u32_u24_e32 v0, 0x8840, v0
	v_lshlrev_b32_e32 v162, 1, v0
	v_sub_co_u32_e32 v8, vcc, v210, v176
	v_lshl_add_u64 v[0:1], s[66:67], 0, v[162:163]
	s_nop 0
	v_subbrev_co_u32_e32 v9, vcc, 0, v122, vcc
	v_lshl_add_u64 v[0:1], v[8:9], 1, v[0:1]
	global_store_dword v[0:1], v3, off offset:352
	s_nop 1
	v_mov_b32_dpp v3, v5 quad_perm:[1,0,3,2] row_mask:0xf bank_mask:0xf
	v_perm_b32 v4, v3, v5, v250
	v_lshl_add_u64 v[0:1], v[0:1], 0, s[42:43]
	v_add_co_u32_e32 v8, vcc, 0x22000, v0
	s_nop 1
	v_addc_co_u32_e32 v9, vcc, 0, v1, vcc
	global_store_dword v[8:9], v4, off offset:256
	s_nop 1
	v_mov_b32_dpp v4, v6 quad_perm:[1,0,3,2] row_mask:0xf bank_mask:0xf
	v_perm_b32 v3, v4, v6, v250
	s_waitcnt lgkmcnt(0)
	s_nop 1
	v_mov_b32_dpp v4, v7 quad_perm:[1,0,3,2] row_mask:0xf bank_mask:0xf
	v_add_co_u32_e32 v8, vcc, 0x44000, v0
	s_nop 1
	v_addc_co_u32_e32 v9, vcc, 0, v1, vcc
	global_store_dword v[8:9], v3, off offset:512
	v_perm_b32 v2, v4, v7, v250
	v_add_co_u32_e32 v0, vcc, 0x66000, v0
	s_nop 1
	v_addc_co_u32_e32 v1, vcc, 0, v1, vcc
	global_store_dword v[0:1], v2, off offset:768
